# P2 v-tile epilogue: lane^16 / lane^32 butterfly by v_permlane16_swap / v_permlane32_swap instead of ds_bpermute (bit-identical sums)
# speedup vs baseline: 1.1036x; 1.0004x over previous
; __device__ __forceinline__ float gelu_tanh(float x) { const float u = 1.5957691216f * (x + 0.044715f * x * x * x); return x * __builtin_amdgcn_rcpf(1.f + __expf(-u)); }
; __device__ __forceinline__ void st_bf16x8(bf16_t* p, const f32x4 a, const f32x4 b) { uint4 o; o.x = cvt_pk_bf16(a[0], a[1]); o.y = cvt_pk_bf16(a[2], a[3]); o.z = cvt_pk_bf16(b[0], b[1]); o.w = cvt_pk_bf16(b[2], b[3]); *(uint4*)p = o; }
;     __device__ __forceinline__ void row(const f32x4 (&a)[2][2], int row, int pn, int wc, int fq) const {
;     ...
;         } else if (pn < 4) {
;             const int head = (pn - 2) * 4 + wc;
;             f32x4 g[2][2]; float ss = 0.f;
; #pragma unroll
;             for (int bj = 0; bj < 2; ++bj)
; #pragma unroll
;                 for (int n = 0; n < 2; ++n)
; #pragma unroll
;                     for (int j = 0; j < 4; ++j) { const float t = gelu_tanh(a[bj][n][j]); g[bj][n][j] = t; ss += t * t; }
;             ss += __shfl_xor(ss, 16); ss += __shfl_xor(ss, 32);
;             const float rs = rsqrtf(ss * (1.f / 64.f) + EPS);
; #pragma unroll
;             for (int bj = 0; bj < 2; ++bj) { const int d = head * 64 + bj * 32 + 8 * fq;
;                 const f32x4 v0 = g[bj][0] * rs * *(const f32x4*)(g_v + d), v1 = g[bj][1] * rs * *(const f32x4*)(g_v + d + 4);
;                 st_bf16x8(pV + (size_t)row * 512 + d, v0, v1);
;                 if (row >= NP && row < NTOK) { float* o = out + O_VS + (size_t)(row - NP) * 512 + d; *(f32x4*)o = v0; *(f32x4*)(o + 4) = v1; } }
.LBB0_218:
	s_andn2_b64 vcc, exec, s[0:1]
	s_cbranch_vccnz .LBB0_223
	v_mov_b32_e32 v190, 0x3d372713
	v_mov_b32_e32 v192, 0xbfcc422a
	v_mov_b32_e32 v194, 0x3fb8aa3b
	v_pk_mul_f32 v[128:129], v[124:125], v[190:191] op_sel_hi:[1,0]
	v_pk_mul_f32 v[132:133], v[126:127], v[190:191] op_sel_hi:[1,0]
	v_pk_mul_f32 v[158:159], v[120:121], v[190:191] op_sel_hi:[1,0]
	v_pk_mul_f32 v[160:161], v[122:123], v[190:191] op_sel_hi:[1,0]
	v_pk_mul_f32 v[162:163], v[116:117], v[190:191] op_sel_hi:[1,0]
	v_pk_mul_f32 v[164:165], v[118:119], v[190:191] op_sel_hi:[1,0]
	v_pk_mul_f32 v[166:167], v[112:113], v[190:191] op_sel_hi:[1,0]
	v_pk_mul_f32 v[168:169], v[114:115], v[190:191] op_sel_hi:[1,0]
	v_pk_mul_f32 v[128:129], v[124:125], v[128:129]
	v_pk_mul_f32 v[132:133], v[126:127], v[132:133]
	v_pk_mul_f32 v[158:159], v[120:121], v[158:159]
	v_pk_mul_f32 v[160:161], v[122:123], v[160:161]
	v_pk_mul_f32 v[162:163], v[116:117], v[162:163]
	v_pk_mul_f32 v[164:165], v[118:119], v[164:165]
	v_pk_mul_f32 v[166:167], v[112:113], v[166:167]
	v_pk_mul_f32 v[168:169], v[114:115], v[168:169]
	v_pk_fma_f32 v[128:129], v[124:125], v[128:129], v[124:125]
	v_pk_fma_f32 v[132:133], v[126:127], v[132:133], v[126:127]
	v_pk_fma_f32 v[158:159], v[120:121], v[158:159], v[120:121]
	v_pk_fma_f32 v[160:161], v[122:123], v[160:161], v[122:123]
	v_pk_fma_f32 v[162:163], v[116:117], v[162:163], v[116:117]
	v_pk_fma_f32 v[164:165], v[118:119], v[164:165], v[118:119]
	v_pk_fma_f32 v[166:167], v[112:113], v[166:167], v[112:113]
	v_pk_fma_f32 v[168:169], v[114:115], v[168:169], v[114:115]
	v_pk_mul_f32 v[128:129], v[128:129], v[192:193] op_sel_hi:[1,0]
	v_pk_mul_f32 v[132:133], v[132:133], v[192:193] op_sel_hi:[1,0]
	v_pk_mul_f32 v[158:159], v[158:159], v[192:193] op_sel_hi:[1,0]
	v_pk_mul_f32 v[160:161], v[160:161], v[192:193] op_sel_hi:[1,0]
	v_pk_mul_f32 v[162:163], v[162:163], v[192:193] op_sel_hi:[1,0]
	v_pk_mul_f32 v[164:165], v[164:165], v[192:193] op_sel_hi:[1,0]
	v_pk_mul_f32 v[166:167], v[166:167], v[192:193] op_sel_hi:[1,0]
	v_pk_mul_f32 v[168:169], v[168:169], v[192:193] op_sel_hi:[1,0]
	v_pk_mul_f32 v[128:129], v[128:129], v[194:195] op_sel_hi:[1,0]
	v_pk_mul_f32 v[132:133], v[132:133], v[194:195] op_sel_hi:[1,0]
	v_pk_mul_f32 v[158:159], v[158:159], v[194:195] op_sel_hi:[1,0]
	v_pk_mul_f32 v[160:161], v[160:161], v[194:195] op_sel_hi:[1,0]
	v_pk_mul_f32 v[162:163], v[162:163], v[194:195] op_sel_hi:[1,0]
	v_pk_mul_f32 v[164:165], v[164:165], v[194:195] op_sel_hi:[1,0]
	v_pk_mul_f32 v[166:167], v[166:167], v[194:195] op_sel_hi:[1,0]
	v_pk_mul_f32 v[168:169], v[168:169], v[194:195] op_sel_hi:[1,0]
	v_exp_f32_e32 v128, v128
	v_exp_f32_e32 v129, v129
	v_exp_f32_e32 v132, v132
	v_exp_f32_e32 v133, v133
	v_exp_f32_e32 v158, v158
	v_exp_f32_e32 v159, v159
	v_exp_f32_e32 v160, v160
	v_exp_f32_e32 v161, v161
	v_exp_f32_e32 v162, v162
	v_exp_f32_e32 v163, v163
	v_exp_f32_e32 v164, v164
	v_exp_f32_e32 v165, v165
	v_exp_f32_e32 v166, v166
	v_exp_f32_e32 v167, v167
	v_exp_f32_e32 v168, v168
	v_exp_f32_e32 v169, v169
	v_pk_add_f32 v[128:129], v[128:129], 1.0 op_sel_hi:[1,0]
	v_pk_add_f32 v[132:133], v[132:133], 1.0 op_sel_hi:[1,0]
	v_pk_add_f32 v[158:159], v[158:159], 1.0 op_sel_hi:[1,0]
	v_pk_add_f32 v[160:161], v[160:161], 1.0 op_sel_hi:[1,0]
	v_pk_add_f32 v[162:163], v[162:163], 1.0 op_sel_hi:[1,0]
	v_pk_add_f32 v[164:165], v[164:165], 1.0 op_sel_hi:[1,0]
	v_pk_add_f32 v[166:167], v[166:167], 1.0 op_sel_hi:[1,0]
	v_pk_add_f32 v[168:169], v[168:169], 1.0 op_sel_hi:[1,0]
	v_rcp_f32_e32 v128, v128
	v_rcp_f32_e32 v129, v129
	v_rcp_f32_e32 v132, v132
	v_rcp_f32_e32 v133, v133
	v_rcp_f32_e32 v158, v158
	v_rcp_f32_e32 v159, v159
	v_rcp_f32_e32 v160, v160
	v_rcp_f32_e32 v161, v161
	v_rcp_f32_e32 v162, v162
	v_rcp_f32_e32 v163, v163
	v_rcp_f32_e32 v164, v164
	v_rcp_f32_e32 v165, v165
	v_rcp_f32_e32 v166, v166
	v_rcp_f32_e32 v167, v167
	v_rcp_f32_e32 v168, v168
	v_rcp_f32_e32 v169, v169
	v_pk_mul_f32 v[128:129], v[124:125], v[128:129]
	v_pk_mul_f32 v[132:133], v[126:127], v[132:133]
	v_pk_mul_f32 v[158:159], v[120:121], v[158:159]
	v_pk_mul_f32 v[160:161], v[122:123], v[160:161]
	v_pk_mul_f32 v[162:163], v[116:117], v[162:163]
	v_pk_mul_f32 v[164:165], v[118:119], v[164:165]
	v_pk_mul_f32 v[166:167], v[112:113], v[166:167]
	v_pk_mul_f32 v[168:169], v[114:115], v[168:169]
	v_pk_mul_f32 v[130:131], v[128:129], v[128:129]
	v_pk_mul_f32 v[134:135], v[132:133], v[132:133]
	v_add_f32_e32 v130, v130, v131
	v_add_f32_e32 v130, v134, v130
	v_pk_mul_f32 v[170:171], v[158:159], v[158:159]
	v_add_f32_e32 v130, v135, v130
	v_add_f32_e32 v130, v170, v130
	v_pk_mul_f32 v[172:173], v[160:161], v[160:161]
	v_add_f32_e32 v130, v171, v130
	v_add_f32_e32 v130, v172, v130
	v_pk_mul_f32 v[174:175], v[162:163], v[162:163]
	v_add_f32_e32 v130, v173, v130
	v_add_f32_e32 v130, v130, v174
	v_pk_mul_f32 v[176:177], v[164:165], v[164:165]
	v_add_f32_e32 v130, v175, v130
	v_add_f32_e32 v130, v176, v130
	v_pk_mul_f32 v[178:179], v[166:167], v[166:167]
	v_add_f32_e32 v130, v177, v130
	v_add_f32_e32 v130, v178, v130
	v_pk_mul_f32 v[180:181], v[168:169], v[168:169]
	v_add_f32_e32 v130, v179, v130
	v_add_f32_e32 v130, v180, v130
	v_add_f32_e32 v130, v181, v130
	v_mov_b32_e32 v131, v130
	s_nop 1
	v_permlane16_swap_b32 v130, v131
	v_lshl_add_u64 v[180:181], v[140:141], 2, s[18:19]
	v_ashrrev_i32_e32 v157, 31, v156
	v_lshlrev_b64 v[174:175], 10, v[156:157]
	v_lshlrev_b32_e32 v172, 9, v156
	s_waitcnt lgkmcnt(0)
	v_add_f32_e32 v130, v130, v131
	v_mov_b32_e32 v131, v130
	s_nop 1
	v_permlane32_swap_b32 v130, v131
	v_mov_b32_e32 v173, v141
	v_cndmask_b32_e64 v157, 0, 1, s[10:11]
	v_cmp_ne_u32_e64 s[0:1], 1, v157
	s_waitcnt lgkmcnt(0)
	v_add_f32_e32 v130, v130, v131
	v_fmamk_f32 v130, v130, 0x3c800000, v188
	v_cmp_gt_f32_e32 vcc, s13, v130
	v_mul_f32_e32 v131, 0x4b800000, v130
	s_nop 0
	v_cndmask_b32_e32 v130, v130, v131, vcc
	v_rsq_f32_e32 v130, v130
	s_nop 0
	v_mul_f32_e32 v131, 0x45800000, v130
	v_cndmask_b32_e32 v170, v130, v131, vcc
	v_pk_mul_f32 v[176:177], v[128:129], v[170:171] op_sel_hi:[1,0]
	v_pk_mul_f32 v[178:179], v[132:133], v[170:171] op_sel_hi:[1,0]
	s_waitcnt vmcnt(0)
	v_mov_b64_e32 v[128:129], v[208:209]
	v_mov_b64_e32 v[130:131], v[210:211]
	v_mov_b64_e32 v[132:133], v[204:205]
	v_mov_b64_e32 v[134:135], v[206:207]
	v_pk_mul_f32 v[158:159], v[158:159], v[170:171] op_sel_hi:[1,0]
	v_pk_mul_f32 v[160:161], v[160:161], v[170:171] op_sel_hi:[1,0]
	s_andn2_b64 vcc, exec, s[10:11]
	v_pk_mul_f32 v[128:129], v[128:129], v[158:159]
	v_lshl_add_u64 v[158:159], s[46:47], 0, v[174:175]
	v_pk_mul_f32 v[134:135], v[134:135], v[178:179]
	v_pk_mul_f32 v[132:133], v[132:133], v[176:177]
	v_pk_mul_f32 v[130:131], v[130:131], v[160:161]
	v_lshl_add_u64 v[158:159], v[140:141], 1, v[158:159]
	v_lshl_add_u64 v[160:161], v[172:173], 2, s[56:57]
	v_cvt_pk_bf16_f32 v174, v132, v133
	v_cvt_pk_bf16_f32 v175, v134, v135
	v_cvt_pk_bf16_f32 v176, v128, v129
	v_cvt_pk_bf16_f32 v177, v130, v131
	global_store_dwordx4 v[158:159], v[174:177], off
	s_cbranch_vccnz .LBB0_221
;     __device__ __forceinline__ void row(const f32x4 (&a)[2][2], int row, int pn, int wc, int fq) const {
;     ...
;                 if (row >= NP && row < NTOK) { float* o = out + O_VS + (size_t)(row - NP) * 512 + d; *(f32x4*)o = v0; *(f32x4*)(o + 4) = v1; } }
	v_lshl_add_u64 v[172:173], v[140:141], 2, v[160:161]
	v_lshl_add_u64 v[174:175], v[172:173], 0, s[70:71]
	v_add_co_u32_e32 v172, vcc, 0x2108000, v172
	s_nop 1
	v_addc_co_u32_e32 v173, vcc, 0, v173, vcc
	global_store_dwordx4 v[172:173], v[132:135], off
	global_store_dwordx4 v[174:175], v[128:131], off offset:16

; __device__ __forceinline__ float gelu_tanh(float x) { const float u = 1.5957691216f * (x + 0.044715f * x * x * x); return x * __builtin_amdgcn_rcpf(1.f + __expf(-u)); }
; __device__ __forceinline__ void st_bf16x8(bf16_t* p, const f32x4 a, const f32x4 b) { uint4 o; o.x = cvt_pk_bf16(a[0], a[1]); o.y = cvt_pk_bf16(a[2], a[3]); o.z = cvt_pk_bf16(b[0], b[1]); o.w = cvt_pk_bf16(b[2], b[3]); *(uint4*)p = o; }
;     __device__ __forceinline__ void row(const f32x4 (&a)[2][2], int row, int pn, int wc, int fq) const {
;     ...
;         } else if (pn < 4) {
;             const int head = (pn - 2) * 4 + wc;
;             f32x4 g[2][2]; float ss = 0.f;
; #pragma unroll
;             for (int bj = 0; bj < 2; ++bj)
; #pragma unroll
;                 for (int n = 0; n < 2; ++n)
; #pragma unroll
;                     for (int j = 0; j < 4; ++j) { const float t = gelu_tanh(a[bj][n][j]); g[bj][n][j] = t; ss += t * t; }
;             ss += __shfl_xor(ss, 16); ss += __shfl_xor(ss, 32);
;             const float rs = rsqrtf(ss * (1.f / 64.f) + EPS);
; #pragma unroll
;             for (int bj = 0; bj < 2; ++bj) { const int d = head * 64 + bj * 32 + 8 * fq;
;                 const f32x4 v0 = g[bj][0] * rs * *(const f32x4*)(g_v + d), v1 = g[bj][1] * rs * *(const f32x4*)(g_v + d + 4);
;                 st_bf16x8(pV + (size_t)row * 512 + d, v0, v1);
;                 if (row >= NP && row < NTOK) { float* o = out + O_VS + (size_t)(row - NP) * 512 + d; *(f32x4*)o = v0; *(f32x4*)(o + 4) = v1; } }
.LBB0_240:
	s_andn2_b64 vcc, exec, s[0:1]
	s_cbranch_vccnz .LBB0_245
	v_mov_b32_e32 v190, 0x3d372713
	v_mov_b32_e32 v192, 0xbfcc422a
	v_mov_b32_e32 v194, 0x3fb8aa3b
	v_pk_mul_f32 v[112:113], v[108:109], v[190:191] op_sel_hi:[1,0]
	v_pk_mul_f32 v[116:117], v[110:111], v[190:191] op_sel_hi:[1,0]
	v_pk_mul_f32 v[122:123], v[104:105], v[190:191] op_sel_hi:[1,0]
	v_pk_mul_f32 v[124:125], v[106:107], v[190:191] op_sel_hi:[1,0]
	v_pk_mul_f32 v[126:127], v[100:101], v[190:191] op_sel_hi:[1,0]
	v_pk_mul_f32 v[128:129], v[102:103], v[190:191] op_sel_hi:[1,0]
	v_pk_mul_f32 v[130:131], v[96:97], v[190:191] op_sel_hi:[1,0]
	v_pk_mul_f32 v[132:133], v[98:99], v[190:191] op_sel_hi:[1,0]
	v_pk_mul_f32 v[112:113], v[108:109], v[112:113]
	v_pk_mul_f32 v[116:117], v[110:111], v[116:117]
	v_pk_mul_f32 v[122:123], v[104:105], v[122:123]
	v_pk_mul_f32 v[124:125], v[106:107], v[124:125]
	v_pk_mul_f32 v[126:127], v[100:101], v[126:127]
	v_pk_mul_f32 v[128:129], v[102:103], v[128:129]
	v_pk_mul_f32 v[130:131], v[96:97], v[130:131]
	v_pk_mul_f32 v[132:133], v[98:99], v[132:133]
	v_pk_fma_f32 v[112:113], v[108:109], v[112:113], v[108:109]
	v_pk_fma_f32 v[116:117], v[110:111], v[116:117], v[110:111]
	v_pk_fma_f32 v[122:123], v[104:105], v[122:123], v[104:105]
	v_pk_fma_f32 v[124:125], v[106:107], v[124:125], v[106:107]
	v_pk_fma_f32 v[126:127], v[100:101], v[126:127], v[100:101]
	v_pk_fma_f32 v[128:129], v[102:103], v[128:129], v[102:103]
	v_pk_fma_f32 v[130:131], v[96:97], v[130:131], v[96:97]
	v_pk_fma_f32 v[132:133], v[98:99], v[132:133], v[98:99]
	v_pk_mul_f32 v[112:113], v[112:113], v[192:193] op_sel_hi:[1,0]
	v_pk_mul_f32 v[116:117], v[116:117], v[192:193] op_sel_hi:[1,0]
	v_pk_mul_f32 v[122:123], v[122:123], v[192:193] op_sel_hi:[1,0]
	v_pk_mul_f32 v[124:125], v[124:125], v[192:193] op_sel_hi:[1,0]
	v_pk_mul_f32 v[126:127], v[126:127], v[192:193] op_sel_hi:[1,0]
	v_pk_mul_f32 v[128:129], v[128:129], v[192:193] op_sel_hi:[1,0]
	v_pk_mul_f32 v[130:131], v[130:131], v[192:193] op_sel_hi:[1,0]
	v_pk_mul_f32 v[132:133], v[132:133], v[192:193] op_sel_hi:[1,0]
	v_pk_mul_f32 v[112:113], v[112:113], v[194:195] op_sel_hi:[1,0]
	v_pk_mul_f32 v[116:117], v[116:117], v[194:195] op_sel_hi:[1,0]
	v_pk_mul_f32 v[122:123], v[122:123], v[194:195] op_sel_hi:[1,0]
	v_pk_mul_f32 v[124:125], v[124:125], v[194:195] op_sel_hi:[1,0]
	v_pk_mul_f32 v[126:127], v[126:127], v[194:195] op_sel_hi:[1,0]
	v_pk_mul_f32 v[128:129], v[128:129], v[194:195] op_sel_hi:[1,0]
	v_pk_mul_f32 v[130:131], v[130:131], v[194:195] op_sel_hi:[1,0]
	v_pk_mul_f32 v[132:133], v[132:133], v[194:195] op_sel_hi:[1,0]
	v_exp_f32_e32 v112, v112
	v_exp_f32_e32 v113, v113
	v_exp_f32_e32 v116, v116
	v_exp_f32_e32 v117, v117
	v_exp_f32_e32 v122, v122
	v_exp_f32_e32 v123, v123
	v_exp_f32_e32 v124, v124
	v_exp_f32_e32 v125, v125
	v_exp_f32_e32 v126, v126
	v_exp_f32_e32 v127, v127
	v_exp_f32_e32 v128, v128
	v_exp_f32_e32 v129, v129
	v_exp_f32_e32 v130, v130
	v_exp_f32_e32 v131, v131
	v_exp_f32_e32 v132, v132
	v_exp_f32_e32 v133, v133
	v_pk_add_f32 v[112:113], v[112:113], 1.0 op_sel_hi:[1,0]
	v_pk_add_f32 v[116:117], v[116:117], 1.0 op_sel_hi:[1,0]
	v_pk_add_f32 v[122:123], v[122:123], 1.0 op_sel_hi:[1,0]
	v_pk_add_f32 v[124:125], v[124:125], 1.0 op_sel_hi:[1,0]
	v_pk_add_f32 v[126:127], v[126:127], 1.0 op_sel_hi:[1,0]
	v_pk_add_f32 v[128:129], v[128:129], 1.0 op_sel_hi:[1,0]
	v_pk_add_f32 v[130:131], v[130:131], 1.0 op_sel_hi:[1,0]
	v_pk_add_f32 v[132:133], v[132:133], 1.0 op_sel_hi:[1,0]
	v_rcp_f32_e32 v112, v112
	v_rcp_f32_e32 v113, v113
	v_rcp_f32_e32 v116, v116
	v_rcp_f32_e32 v117, v117
	v_rcp_f32_e32 v122, v122
	v_rcp_f32_e32 v123, v123
	v_rcp_f32_e32 v124, v124
	v_rcp_f32_e32 v125, v125
	v_rcp_f32_e32 v126, v126
	v_rcp_f32_e32 v127, v127
	v_rcp_f32_e32 v128, v128
	v_rcp_f32_e32 v129, v129
	v_rcp_f32_e32 v130, v130
	v_rcp_f32_e32 v131, v131
	v_rcp_f32_e32 v132, v132
	v_rcp_f32_e32 v133, v133
	v_pk_mul_f32 v[112:113], v[108:109], v[112:113]
	v_pk_mul_f32 v[116:117], v[110:111], v[116:117]
	v_pk_mul_f32 v[122:123], v[104:105], v[122:123]
	v_pk_mul_f32 v[124:125], v[106:107], v[124:125]
	v_pk_mul_f32 v[126:127], v[100:101], v[126:127]
	v_pk_mul_f32 v[128:129], v[102:103], v[128:129]
	v_pk_mul_f32 v[130:131], v[96:97], v[130:131]
	v_pk_mul_f32 v[132:133], v[98:99], v[132:133]
	v_pk_mul_f32 v[114:115], v[112:113], v[112:113]
	v_pk_mul_f32 v[118:119], v[116:117], v[116:117]
	v_add_f32_e32 v114, v114, v115
	v_add_f32_e32 v114, v118, v114
	v_pk_mul_f32 v[134:135], v[122:123], v[122:123]
	v_add_f32_e32 v114, v119, v114
	v_add_f32_e32 v114, v134, v114
	v_pk_mul_f32 v[158:159], v[124:125], v[124:125]
	v_add_f32_e32 v114, v135, v114
	v_add_f32_e32 v114, v158, v114
	v_pk_mul_f32 v[160:161], v[126:127], v[126:127]
	v_add_f32_e32 v114, v159, v114
	v_add_f32_e32 v114, v114, v160
	v_pk_mul_f32 v[162:163], v[128:129], v[128:129]
	v_add_f32_e32 v114, v161, v114
	v_add_f32_e32 v114, v162, v114
	v_pk_mul_f32 v[164:165], v[130:131], v[130:131]
	v_add_f32_e32 v114, v163, v114
	v_add_f32_e32 v114, v164, v114
	v_pk_mul_f32 v[166:167], v[132:133], v[132:133]
	v_add_f32_e32 v114, v165, v114
	v_add_f32_e32 v114, v166, v114
	v_add_f32_e32 v114, v167, v114
	v_mov_b32_e32 v115, v114
	s_nop 1
	v_permlane16_swap_b32 v114, v115
	v_lshl_add_u64 v[166:167], v[140:141], 2, s[18:19]
	v_ashrrev_i32_e32 v121, 31, v120
	v_lshlrev_b64 v[160:161], 10, v[120:121]
	v_lshlrev_b32_e32 v158, 9, v120
	s_waitcnt lgkmcnt(0)
	v_add_f32_e32 v114, v114, v115
	v_mov_b32_e32 v115, v114
	s_nop 1
	v_permlane32_swap_b32 v114, v115
	v_mov_b32_e32 v159, v141
	v_cndmask_b32_e64 v121, 0, 1, s[10:11]
	v_cmp_ne_u32_e64 s[0:1], 1, v121
	s_waitcnt lgkmcnt(0)
	v_add_f32_e32 v114, v114, v115
	v_fmamk_f32 v114, v114, 0x3c800000, v188
	v_cmp_gt_f32_e32 vcc, s13, v114
	v_mul_f32_e32 v115, 0x4b800000, v114
	s_nop 0
	v_cndmask_b32_e32 v114, v114, v115, vcc
	v_rsq_f32_e32 v114, v114
	s_nop 0
	v_mul_f32_e32 v115, 0x45800000, v114
	v_cndmask_b32_e32 v134, v114, v115, vcc
	v_pk_mul_f32 v[162:163], v[112:113], v[134:135] op_sel_hi:[1,0]
	v_pk_mul_f32 v[164:165], v[116:117], v[134:135] op_sel_hi:[1,0]
	v_mov_b64_e32 v[112:113], v[208:209]
	v_mov_b64_e32 v[114:115], v[210:211]
	v_mov_b64_e32 v[116:117], v[204:205]
	v_mov_b64_e32 v[118:119], v[206:207]
	v_pk_mul_f32 v[122:123], v[122:123], v[134:135] op_sel_hi:[1,0]
	v_pk_mul_f32 v[124:125], v[124:125], v[134:135] op_sel_hi:[1,0]
	s_andn2_b64 vcc, exec, s[10:11]
	v_pk_mul_f32 v[112:113], v[112:113], v[122:123]
	v_lshl_add_u64 v[122:123], s[46:47], 0, v[160:161]
	v_pk_mul_f32 v[118:119], v[118:119], v[164:165]
	v_pk_mul_f32 v[116:117], v[116:117], v[162:163]
	v_pk_mul_f32 v[114:115], v[114:115], v[124:125]
	v_lshl_add_u64 v[122:123], v[140:141], 1, v[122:123]
	v_lshl_add_u64 v[124:125], v[158:159], 2, s[56:57]
	v_cvt_pk_bf16_f32 v160, v116, v117
	v_cvt_pk_bf16_f32 v161, v118, v119
	v_cvt_pk_bf16_f32 v162, v112, v113
	v_cvt_pk_bf16_f32 v163, v114, v115
	global_store_dwordx4 v[122:123], v[160:163], off
	s_cbranch_vccnz .LBB0_243
;     __device__ __forceinline__ void row(const f32x4 (&a)[2][2], int row, int pn, int wc, int fq) const {
;     ...
;                 if (row >= NP && row < NTOK) { float* o = out + O_VS + (size_t)(row - NP) * 512 + d; *(f32x4*)o = v0; *(f32x4*)(o + 4) = v1; } }
	v_lshl_add_u64 v[158:159], v[140:141], 2, v[124:125]
	v_lshl_add_u64 v[160:161], v[158:159], 0, s[70:71]
	v_add_co_u32_e32 v158, vcc, 0x2108000, v158
	s_nop 1
	v_addc_co_u32_e32 v159, vcc, 0, v159, vcc
	global_store_dwordx4 v[158:159], v[116:119], off
	global_store_dwordx4 v[160:161], v[112:115], off offset:16

; __device__ __forceinline__ float gelu_tanh(float x) { const float u = 1.5957691216f * (x + 0.044715f * x * x * x); return x * __builtin_amdgcn_rcpf(1.f + __expf(-u)); }
; __device__ __forceinline__ void st_bf16x8(bf16_t* p, const f32x4 a, const f32x4 b) { uint4 o; o.x = cvt_pk_bf16(a[0], a[1]); o.y = cvt_pk_bf16(a[2], a[3]); o.z = cvt_pk_bf16(b[0], b[1]); o.w = cvt_pk_bf16(b[2], b[3]); *(uint4*)p = o; }
;     __device__ __forceinline__ void row(const f32x4 (&a)[2][2], int row, int pn, int wc, int fq) const {
;     ...
;         } else if (pn < 4) {
;             const int head = (pn - 2) * 4 + wc;
;             f32x4 g[2][2]; float ss = 0.f;
; #pragma unroll
;             for (int bj = 0; bj < 2; ++bj)
; #pragma unroll
;                 for (int n = 0; n < 2; ++n)
; #pragma unroll
;                     for (int j = 0; j < 4; ++j) { const float t = gelu_tanh(a[bj][n][j]); g[bj][n][j] = t; ss += t * t; }
;             ss += __shfl_xor(ss, 16); ss += __shfl_xor(ss, 32);
;             const float rs = rsqrtf(ss * (1.f / 64.f) + EPS);
; #pragma unroll
;             for (int bj = 0; bj < 2; ++bj) { const int d = head * 64 + bj * 32 + 8 * fq;
;                 const f32x4 v0 = g[bj][0] * rs * *(const f32x4*)(g_v + d), v1 = g[bj][1] * rs * *(const f32x4*)(g_v + d + 4);
;                 st_bf16x8(pV + (size_t)row * 512 + d, v0, v1);
;                 if (row >= NP && row < NTOK) { float* o = out + O_VS + (size_t)(row - NP) * 512 + d; *(f32x4*)o = v0; *(f32x4*)(o + 4) = v1; } }
.LBB0_255:
	s_andn2_b64 vcc, exec, s[0:1]
	s_cbranch_vccnz .LBB0_260
	v_mov_b32_e32 v190, 0x3d372713
	v_mov_b32_e32 v192, 0xbfcc422a
	v_mov_b32_e32 v194, 0x3fb8aa3b
	v_pk_mul_f32 v[96:97], v[92:93], v[190:191] op_sel_hi:[1,0]
	v_pk_mul_f32 v[100:101], v[94:95], v[190:191] op_sel_hi:[1,0]
	v_pk_mul_f32 v[106:107], v[88:89], v[190:191] op_sel_hi:[1,0]
	v_pk_mul_f32 v[108:109], v[90:91], v[190:191] op_sel_hi:[1,0]
	v_pk_mul_f32 v[110:111], v[84:85], v[190:191] op_sel_hi:[1,0]
	v_pk_mul_f32 v[112:113], v[86:87], v[190:191] op_sel_hi:[1,0]
	v_pk_mul_f32 v[114:115], v[80:81], v[190:191] op_sel_hi:[1,0]
	v_pk_mul_f32 v[116:117], v[82:83], v[190:191] op_sel_hi:[1,0]
	v_pk_mul_f32 v[96:97], v[92:93], v[96:97]
	v_pk_mul_f32 v[100:101], v[94:95], v[100:101]
	v_pk_mul_f32 v[106:107], v[88:89], v[106:107]
	v_pk_mul_f32 v[108:109], v[90:91], v[108:109]
	v_pk_mul_f32 v[110:111], v[84:85], v[110:111]
	v_pk_mul_f32 v[112:113], v[86:87], v[112:113]
	v_pk_mul_f32 v[114:115], v[80:81], v[114:115]
	v_pk_mul_f32 v[116:117], v[82:83], v[116:117]
	v_pk_fma_f32 v[96:97], v[92:93], v[96:97], v[92:93]
	v_pk_fma_f32 v[100:101], v[94:95], v[100:101], v[94:95]
	v_pk_fma_f32 v[106:107], v[88:89], v[106:107], v[88:89]
	v_pk_fma_f32 v[108:109], v[90:91], v[108:109], v[90:91]
	v_pk_fma_f32 v[110:111], v[84:85], v[110:111], v[84:85]
	v_pk_fma_f32 v[112:113], v[86:87], v[112:113], v[86:87]
	v_pk_fma_f32 v[114:115], v[80:81], v[114:115], v[80:81]
	v_pk_fma_f32 v[116:117], v[82:83], v[116:117], v[82:83]
	v_pk_mul_f32 v[96:97], v[96:97], v[192:193] op_sel_hi:[1,0]
	v_pk_mul_f32 v[100:101], v[100:101], v[192:193] op_sel_hi:[1,0]
	v_pk_mul_f32 v[106:107], v[106:107], v[192:193] op_sel_hi:[1,0]
	v_pk_mul_f32 v[108:109], v[108:109], v[192:193] op_sel_hi:[1,0]
	v_pk_mul_f32 v[110:111], v[110:111], v[192:193] op_sel_hi:[1,0]
	v_pk_mul_f32 v[112:113], v[112:113], v[192:193] op_sel_hi:[1,0]
	v_pk_mul_f32 v[114:115], v[114:115], v[192:193] op_sel_hi:[1,0]
	v_pk_mul_f32 v[116:117], v[116:117], v[192:193] op_sel_hi:[1,0]
	v_pk_mul_f32 v[96:97], v[96:97], v[194:195] op_sel_hi:[1,0]
	v_pk_mul_f32 v[100:101], v[100:101], v[194:195] op_sel_hi:[1,0]
	v_pk_mul_f32 v[106:107], v[106:107], v[194:195] op_sel_hi:[1,0]
	v_pk_mul_f32 v[108:109], v[108:109], v[194:195] op_sel_hi:[1,0]
	v_pk_mul_f32 v[110:111], v[110:111], v[194:195] op_sel_hi:[1,0]
	v_pk_mul_f32 v[112:113], v[112:113], v[194:195] op_sel_hi:[1,0]
	v_pk_mul_f32 v[114:115], v[114:115], v[194:195] op_sel_hi:[1,0]
	v_pk_mul_f32 v[116:117], v[116:117], v[194:195] op_sel_hi:[1,0]
	v_exp_f32_e32 v96, v96
	v_exp_f32_e32 v97, v97
	v_exp_f32_e32 v100, v100
	v_exp_f32_e32 v101, v101
	v_exp_f32_e32 v106, v106
	v_exp_f32_e32 v107, v107
	v_exp_f32_e32 v108, v108
	v_exp_f32_e32 v109, v109
	v_exp_f32_e32 v110, v110
	v_exp_f32_e32 v111, v111
	v_exp_f32_e32 v112, v112
	v_exp_f32_e32 v113, v113
	v_exp_f32_e32 v114, v114
	v_exp_f32_e32 v115, v115
	v_exp_f32_e32 v116, v116
	v_exp_f32_e32 v117, v117
	v_pk_add_f32 v[96:97], v[96:97], 1.0 op_sel_hi:[1,0]
	v_pk_add_f32 v[100:101], v[100:101], 1.0 op_sel_hi:[1,0]
	v_pk_add_f32 v[106:107], v[106:107], 1.0 op_sel_hi:[1,0]
	v_pk_add_f32 v[108:109], v[108:109], 1.0 op_sel_hi:[1,0]
	v_pk_add_f32 v[110:111], v[110:111], 1.0 op_sel_hi:[1,0]
	v_pk_add_f32 v[112:113], v[112:113], 1.0 op_sel_hi:[1,0]
	v_pk_add_f32 v[114:115], v[114:115], 1.0 op_sel_hi:[1,0]
	v_pk_add_f32 v[116:117], v[116:117], 1.0 op_sel_hi:[1,0]
	v_rcp_f32_e32 v96, v96
	v_rcp_f32_e32 v97, v97
	v_rcp_f32_e32 v100, v100
	v_rcp_f32_e32 v101, v101
	v_rcp_f32_e32 v106, v106
	v_rcp_f32_e32 v107, v107
	v_rcp_f32_e32 v108, v108
	v_rcp_f32_e32 v109, v109
	v_rcp_f32_e32 v110, v110
	v_rcp_f32_e32 v111, v111
	v_rcp_f32_e32 v112, v112
	v_rcp_f32_e32 v113, v113
	v_rcp_f32_e32 v114, v114
	v_rcp_f32_e32 v115, v115
	v_rcp_f32_e32 v116, v116
	v_rcp_f32_e32 v117, v117
	v_pk_mul_f32 v[96:97], v[92:93], v[96:97]
	v_pk_mul_f32 v[100:101], v[94:95], v[100:101]
	v_pk_mul_f32 v[106:107], v[88:89], v[106:107]
	v_pk_mul_f32 v[108:109], v[90:91], v[108:109]
	v_pk_mul_f32 v[110:111], v[84:85], v[110:111]
	v_pk_mul_f32 v[112:113], v[86:87], v[112:113]
	v_pk_mul_f32 v[114:115], v[80:81], v[114:115]
	v_pk_mul_f32 v[116:117], v[82:83], v[116:117]
	v_pk_mul_f32 v[98:99], v[96:97], v[96:97]
	v_pk_mul_f32 v[102:103], v[100:101], v[100:101]
	v_add_f32_e32 v98, v98, v99
	v_add_f32_e32 v98, v102, v98
	v_pk_mul_f32 v[118:119], v[106:107], v[106:107]
	v_add_f32_e32 v98, v103, v98
	v_add_f32_e32 v98, v118, v98
	v_pk_mul_f32 v[120:121], v[108:109], v[108:109]
	v_add_f32_e32 v98, v119, v98
	v_add_f32_e32 v98, v120, v98
	v_pk_mul_f32 v[122:123], v[110:111], v[110:111]
	v_add_f32_e32 v98, v121, v98
	v_add_f32_e32 v98, v98, v122
	v_pk_mul_f32 v[124:125], v[112:113], v[112:113]
	v_add_f32_e32 v98, v123, v98
	v_add_f32_e32 v98, v124, v98
	v_pk_mul_f32 v[126:127], v[114:115], v[114:115]
	v_add_f32_e32 v98, v125, v98
	v_add_f32_e32 v98, v126, v98
	v_pk_mul_f32 v[128:129], v[116:117], v[116:117]
	v_add_f32_e32 v98, v127, v98
	v_add_f32_e32 v98, v128, v98
	v_add_f32_e32 v98, v129, v98
	v_mov_b32_e32 v99, v98
	s_nop 1
	v_permlane16_swap_b32 v98, v99
	v_lshl_add_u64 v[128:129], v[140:141], 2, s[18:19]
	v_ashrrev_i32_e32 v105, 31, v104
	v_lshlrev_b64 v[122:123], 10, v[104:105]
	v_lshlrev_b32_e32 v120, 9, v104
	s_waitcnt lgkmcnt(0)
	v_add_f32_e32 v98, v98, v99
	v_mov_b32_e32 v99, v98
	s_nop 1
	v_permlane32_swap_b32 v98, v99
	v_mov_b32_e32 v121, v141
	v_cndmask_b32_e64 v105, 0, 1, s[10:11]
	v_cmp_ne_u32_e64 s[0:1], 1, v105
	s_waitcnt lgkmcnt(0)
	v_add_f32_e32 v98, v98, v99
	v_fmamk_f32 v98, v98, 0x3c800000, v188
	v_cmp_gt_f32_e32 vcc, s13, v98
	v_mul_f32_e32 v99, 0x4b800000, v98
	s_nop 0
	v_cndmask_b32_e32 v98, v98, v99, vcc
	v_rsq_f32_e32 v98, v98
	s_nop 0
	v_mul_f32_e32 v99, 0x45800000, v98
	v_cndmask_b32_e32 v118, v98, v99, vcc
	v_pk_mul_f32 v[124:125], v[96:97], v[118:119] op_sel_hi:[1,0]
	v_pk_mul_f32 v[126:127], v[100:101], v[118:119] op_sel_hi:[1,0]
	v_mov_b64_e32 v[96:97], v[208:209]
	v_mov_b64_e32 v[98:99], v[210:211]
	v_mov_b64_e32 v[100:101], v[204:205]
	v_mov_b64_e32 v[102:103], v[206:207]
	v_pk_mul_f32 v[106:107], v[106:107], v[118:119] op_sel_hi:[1,0]
	v_pk_mul_f32 v[108:109], v[108:109], v[118:119] op_sel_hi:[1,0]
	s_andn2_b64 vcc, exec, s[10:11]
	v_pk_mul_f32 v[96:97], v[96:97], v[106:107]
	v_lshl_add_u64 v[106:107], s[46:47], 0, v[122:123]
	v_pk_mul_f32 v[102:103], v[102:103], v[126:127]
	v_pk_mul_f32 v[100:101], v[100:101], v[124:125]
	v_pk_mul_f32 v[98:99], v[98:99], v[108:109]
	v_lshl_add_u64 v[106:107], v[140:141], 1, v[106:107]
	v_lshl_add_u64 v[108:109], v[120:121], 2, s[56:57]
	v_cvt_pk_bf16_f32 v122, v100, v101
	v_cvt_pk_bf16_f32 v123, v102, v103
	v_cvt_pk_bf16_f32 v124, v96, v97
	v_cvt_pk_bf16_f32 v125, v98, v99
	global_store_dwordx4 v[106:107], v[122:125], off
	s_cbranch_vccnz .LBB0_258
;     __device__ __forceinline__ void row(const f32x4 (&a)[2][2], int row, int pn, int wc, int fq) const {
;     ...
;                 if (row >= NP && row < NTOK) { float* o = out + O_VS + (size_t)(row - NP) * 512 + d; *(f32x4*)o = v0; *(f32x4*)(o + 4) = v1; } }
	v_lshl_add_u64 v[120:121], v[140:141], 2, v[108:109]
	v_lshl_add_u64 v[122:123], v[120:121], 0, s[70:71]
	v_add_co_u32_e32 v120, vcc, 0x2108000, v120
	s_nop 1
	v_addc_co_u32_e32 v121, vcc, 0, v121, vcc
	global_store_dwordx4 v[120:121], v[100:103], off
	global_store_dwordx4 v[122:123], v[96:99], off offset:16

; __device__ __forceinline__ float gelu_tanh(float x) { const float u = 1.5957691216f * (x + 0.044715f * x * x * x); return x * __builtin_amdgcn_rcpf(1.f + __expf(-u)); }
; __device__ __forceinline__ void st_bf16x8(bf16_t* p, const f32x4 a, const f32x4 b) { uint4 o; o.x = cvt_pk_bf16(a[0], a[1]); o.y = cvt_pk_bf16(a[2], a[3]); o.z = cvt_pk_bf16(b[0], b[1]); o.w = cvt_pk_bf16(b[2], b[3]); *(uint4*)p = o; }
;     __device__ __forceinline__ void row(const f32x4 (&a)[2][2], int row, int pn, int wc, int fq) const {
;     ...
;         } else if (pn < 4) {
;             const int head = (pn - 2) * 4 + wc;
;             f32x4 g[2][2]; float ss = 0.f;
; #pragma unroll
;             for (int bj = 0; bj < 2; ++bj)
; #pragma unroll
;                 for (int n = 0; n < 2; ++n)
; #pragma unroll
;                     for (int j = 0; j < 4; ++j) { const float t = gelu_tanh(a[bj][n][j]); g[bj][n][j] = t; ss += t * t; }
;             ss += __shfl_xor(ss, 16); ss += __shfl_xor(ss, 32);
;             const float rs = rsqrtf(ss * (1.f / 64.f) + EPS);
; #pragma unroll
;             for (int bj = 0; bj < 2; ++bj) { const int d = head * 64 + bj * 32 + 8 * fq;
;                 const f32x4 v0 = g[bj][0] * rs * *(const f32x4*)(g_v + d), v1 = g[bj][1] * rs * *(const f32x4*)(g_v + d + 4);
;                 st_bf16x8(pV + (size_t)row * 512 + d, v0, v1);
;                 if (row >= NP && row < NTOK) { float* o = out + O_VS + (size_t)(row - NP) * 512 + d; *(f32x4*)o = v0; *(f32x4*)(o + 4) = v1; } }
.LBB0_272:
	s_and_b64 vcc, exec, s[0:1]
	s_cbranch_vccz .LBB0_277
	v_mov_b32_e32 v190, 0x3d372713
	v_mov_b32_e32 v192, 0xbfcc422a
	v_mov_b32_e32 v194, 0x3fb8aa3b
	v_pk_mul_f32 v[80:81], v[76:77], v[190:191] op_sel_hi:[1,0]
	v_pk_mul_f32 v[84:85], v[78:79], v[190:191] op_sel_hi:[1,0]
	v_pk_mul_f32 v[90:91], v[72:73], v[190:191] op_sel_hi:[1,0]
	v_pk_mul_f32 v[92:93], v[74:75], v[190:191] op_sel_hi:[1,0]
	v_pk_mul_f32 v[94:95], v[68:69], v[190:191] op_sel_hi:[1,0]
	v_pk_mul_f32 v[96:97], v[70:71], v[190:191] op_sel_hi:[1,0]
	v_pk_mul_f32 v[98:99], v[64:65], v[190:191] op_sel_hi:[1,0]
	v_pk_mul_f32 v[100:101], v[66:67], v[190:191] op_sel_hi:[1,0]
	v_pk_mul_f32 v[80:81], v[76:77], v[80:81]
	v_pk_mul_f32 v[84:85], v[78:79], v[84:85]
	v_pk_mul_f32 v[90:91], v[72:73], v[90:91]
	v_pk_mul_f32 v[92:93], v[74:75], v[92:93]
	v_pk_mul_f32 v[94:95], v[68:69], v[94:95]
	v_pk_mul_f32 v[96:97], v[70:71], v[96:97]
	v_pk_mul_f32 v[98:99], v[64:65], v[98:99]
	v_pk_mul_f32 v[100:101], v[66:67], v[100:101]
	v_pk_fma_f32 v[80:81], v[76:77], v[80:81], v[76:77]
	v_pk_fma_f32 v[84:85], v[78:79], v[84:85], v[78:79]
	v_pk_fma_f32 v[90:91], v[72:73], v[90:91], v[72:73]
	v_pk_fma_f32 v[92:93], v[74:75], v[92:93], v[74:75]
	v_pk_fma_f32 v[94:95], v[68:69], v[94:95], v[68:69]
	v_pk_fma_f32 v[96:97], v[70:71], v[96:97], v[70:71]
	v_pk_fma_f32 v[98:99], v[64:65], v[98:99], v[64:65]
	v_pk_fma_f32 v[100:101], v[66:67], v[100:101], v[66:67]
	v_pk_mul_f32 v[80:81], v[80:81], v[192:193] op_sel_hi:[1,0]
	v_pk_mul_f32 v[84:85], v[84:85], v[192:193] op_sel_hi:[1,0]
	v_pk_mul_f32 v[90:91], v[90:91], v[192:193] op_sel_hi:[1,0]
	v_pk_mul_f32 v[92:93], v[92:93], v[192:193] op_sel_hi:[1,0]
	v_pk_mul_f32 v[94:95], v[94:95], v[192:193] op_sel_hi:[1,0]
	v_pk_mul_f32 v[96:97], v[96:97], v[192:193] op_sel_hi:[1,0]
	v_pk_mul_f32 v[98:99], v[98:99], v[192:193] op_sel_hi:[1,0]
	v_pk_mul_f32 v[100:101], v[100:101], v[192:193] op_sel_hi:[1,0]
	v_pk_mul_f32 v[80:81], v[80:81], v[194:195] op_sel_hi:[1,0]
	v_pk_mul_f32 v[84:85], v[84:85], v[194:195] op_sel_hi:[1,0]
	v_pk_mul_f32 v[90:91], v[90:91], v[194:195] op_sel_hi:[1,0]
	v_pk_mul_f32 v[92:93], v[92:93], v[194:195] op_sel_hi:[1,0]
	v_pk_mul_f32 v[94:95], v[94:95], v[194:195] op_sel_hi:[1,0]
	v_pk_mul_f32 v[96:97], v[96:97], v[194:195] op_sel_hi:[1,0]
	v_pk_mul_f32 v[98:99], v[98:99], v[194:195] op_sel_hi:[1,0]
	v_pk_mul_f32 v[100:101], v[100:101], v[194:195] op_sel_hi:[1,0]
	v_exp_f32_e32 v80, v80
	v_exp_f32_e32 v81, v81
	v_exp_f32_e32 v84, v84
	v_exp_f32_e32 v85, v85
	v_exp_f32_e32 v90, v90
	v_exp_f32_e32 v91, v91
	v_exp_f32_e32 v92, v92
	v_exp_f32_e32 v93, v93
	v_exp_f32_e32 v94, v94
	v_exp_f32_e32 v95, v95
	v_exp_f32_e32 v96, v96
	v_exp_f32_e32 v97, v97
	v_exp_f32_e32 v98, v98
	v_exp_f32_e32 v99, v99
	v_exp_f32_e32 v100, v100
	v_exp_f32_e32 v101, v101
	v_pk_add_f32 v[80:81], v[80:81], 1.0 op_sel_hi:[1,0]
	v_pk_add_f32 v[84:85], v[84:85], 1.0 op_sel_hi:[1,0]
	v_pk_add_f32 v[90:91], v[90:91], 1.0 op_sel_hi:[1,0]
	v_pk_add_f32 v[92:93], v[92:93], 1.0 op_sel_hi:[1,0]
	v_pk_add_f32 v[94:95], v[94:95], 1.0 op_sel_hi:[1,0]
	v_pk_add_f32 v[96:97], v[96:97], 1.0 op_sel_hi:[1,0]
	v_pk_add_f32 v[98:99], v[98:99], 1.0 op_sel_hi:[1,0]
	v_pk_add_f32 v[100:101], v[100:101], 1.0 op_sel_hi:[1,0]
	v_rcp_f32_e32 v80, v80
	v_rcp_f32_e32 v81, v81
	v_rcp_f32_e32 v84, v84
	v_rcp_f32_e32 v85, v85
	v_rcp_f32_e32 v90, v90
	v_rcp_f32_e32 v91, v91
	v_rcp_f32_e32 v92, v92
	v_rcp_f32_e32 v93, v93
	v_rcp_f32_e32 v94, v94
	v_rcp_f32_e32 v95, v95
	v_rcp_f32_e32 v96, v96
	v_rcp_f32_e32 v97, v97
	v_rcp_f32_e32 v98, v98
	v_rcp_f32_e32 v99, v99
	v_rcp_f32_e32 v100, v100
	v_rcp_f32_e32 v101, v101
	v_pk_mul_f32 v[80:81], v[76:77], v[80:81]
	v_pk_mul_f32 v[84:85], v[78:79], v[84:85]
	v_pk_mul_f32 v[90:91], v[72:73], v[90:91]
	v_pk_mul_f32 v[92:93], v[74:75], v[92:93]
	v_pk_mul_f32 v[94:95], v[68:69], v[94:95]
	v_pk_mul_f32 v[96:97], v[70:71], v[96:97]
	v_pk_mul_f32 v[98:99], v[64:65], v[98:99]
	v_pk_mul_f32 v[100:101], v[66:67], v[100:101]
	v_pk_mul_f32 v[82:83], v[80:81], v[80:81]
	v_pk_mul_f32 v[86:87], v[84:85], v[84:85]
	v_add_f32_e32 v82, v82, v83
	v_add_f32_e32 v82, v86, v82
	v_pk_mul_f32 v[102:103], v[90:91], v[90:91]
	v_add_f32_e32 v82, v87, v82
	v_add_f32_e32 v82, v102, v82
	v_pk_mul_f32 v[104:105], v[92:93], v[92:93]
	v_add_f32_e32 v82, v103, v82
	v_add_f32_e32 v82, v104, v82
	v_pk_mul_f32 v[106:107], v[94:95], v[94:95]
	v_add_f32_e32 v82, v105, v82
	v_add_f32_e32 v82, v82, v106
	v_pk_mul_f32 v[108:109], v[96:97], v[96:97]
	v_add_f32_e32 v82, v107, v82
	v_add_f32_e32 v82, v108, v82
	v_pk_mul_f32 v[110:111], v[98:99], v[98:99]
	v_add_f32_e32 v82, v109, v82
	v_add_f32_e32 v82, v110, v82
	v_pk_mul_f32 v[112:113], v[100:101], v[100:101]
	v_add_f32_e32 v82, v111, v82
	v_add_f32_e32 v82, v112, v82
	v_add_f32_e32 v82, v113, v82
	v_mov_b32_e32 v83, v82
	s_nop 1
	v_permlane16_swap_b32 v82, v83
	v_lshl_add_u64 v[112:113], v[140:141], 2, s[18:19]
	v_ashrrev_i32_e32 v89, 31, v88
	v_lshlrev_b64 v[106:107], 10, v[88:89]
	v_lshlrev_b32_e32 v104, 9, v88
	s_waitcnt lgkmcnt(0)
	v_add_f32_e32 v82, v82, v83
	v_mov_b32_e32 v83, v82
	s_nop 1
	v_permlane32_swap_b32 v82, v83
	v_mov_b32_e32 v105, v141
	v_cndmask_b32_e64 v89, 0, 1, s[10:11]
	v_cmp_ne_u32_e64 s[0:1], 1, v89
	s_waitcnt lgkmcnt(0)
	v_add_f32_e32 v82, v82, v83
	v_fmamk_f32 v82, v82, 0x3c800000, v188
	v_cmp_gt_f32_e32 vcc, s13, v82
	v_mul_f32_e32 v83, 0x4b800000, v82
	s_nop 0
	v_cndmask_b32_e32 v82, v82, v83, vcc
	v_rsq_f32_e32 v82, v82
	s_nop 0
	v_mul_f32_e32 v83, 0x45800000, v82
	v_cndmask_b32_e32 v102, v82, v83, vcc
	v_pk_mul_f32 v[108:109], v[80:81], v[102:103] op_sel_hi:[1,0]
	v_pk_mul_f32 v[110:111], v[84:85], v[102:103] op_sel_hi:[1,0]
	v_mov_b64_e32 v[80:81], v[208:209]
	v_mov_b64_e32 v[82:83], v[210:211]
	v_mov_b64_e32 v[84:85], v[204:205]
	v_mov_b64_e32 v[86:87], v[206:207]
	v_pk_mul_f32 v[90:91], v[90:91], v[102:103] op_sel_hi:[1,0]
	v_pk_mul_f32 v[92:93], v[92:93], v[102:103] op_sel_hi:[1,0]
	s_andn2_b64 vcc, exec, s[10:11]
	v_pk_mul_f32 v[80:81], v[80:81], v[90:91]
	v_lshl_add_u64 v[90:91], s[46:47], 0, v[106:107]
	v_pk_mul_f32 v[86:87], v[86:87], v[110:111]
	v_pk_mul_f32 v[84:85], v[84:85], v[108:109]
	v_pk_mul_f32 v[82:83], v[82:83], v[92:93]
	v_lshl_add_u64 v[90:91], v[140:141], 1, v[90:91]
	v_lshl_add_u64 v[92:93], v[104:105], 2, s[56:57]
	v_cvt_pk_bf16_f32 v106, v84, v85
	v_cvt_pk_bf16_f32 v107, v86, v87
	v_cvt_pk_bf16_f32 v108, v80, v81
	v_cvt_pk_bf16_f32 v109, v82, v83
	global_store_dwordx4 v[90:91], v[106:109], off
	s_cbranch_vccnz .LBB0_275
	v_lshl_add_u64 v[104:105], v[140:141], 2, v[92:93]
	v_lshl_add_u64 v[106:107], v[104:105], 0, s[70:71]
	v_add_co_u32_e32 v104, vcc, 0x2108000, v104
	s_nop 1
	v_addc_co_u32_e32 v105, vcc, 0, v105, vcc
	global_store_dwordx4 v[104:105], v[84:87], off
	global_store_dwordx4 v[106:107], v[80:83], off offset:16

; __device__ __forceinline__ float gelu_tanh(float x) { const float u = 1.5957691216f * (x + 0.044715f * x * x * x); return x * __builtin_amdgcn_rcpf(1.f + __expf(-u)); }
; __device__ __forceinline__ void st_bf16x8(bf16_t* p, const f32x4 a, const f32x4 b) { uint4 o; o.x = cvt_pk_bf16(a[0], a[1]); o.y = cvt_pk_bf16(a[2], a[3]); o.z = cvt_pk_bf16(b[0], b[1]); o.w = cvt_pk_bf16(b[2], b[3]); *(uint4*)p = o; }
;     __device__ __forceinline__ void row(const f32x4 (&a)[2][2], int row, int pn, int wc, int fq) const {
;     ...
;         } else if (pn < 4) {
;             const int head = (pn - 2) * 4 + wc;
;             f32x4 g[2][2]; float ss = 0.f;
; #pragma unroll
;             for (int bj = 0; bj < 2; ++bj)
; #pragma unroll
;                 for (int n = 0; n < 2; ++n)
; #pragma unroll
;                     for (int j = 0; j < 4; ++j) { const float t = gelu_tanh(a[bj][n][j]); g[bj][n][j] = t; ss += t * t; }
;             ss += __shfl_xor(ss, 16); ss += __shfl_xor(ss, 32);
;             const float rs = rsqrtf(ss * (1.f / 64.f) + EPS);
; #pragma unroll
;             for (int bj = 0; bj < 2; ++bj) { const int d = head * 64 + bj * 32 + 8 * fq;
;                 const f32x4 v0 = g[bj][0] * rs * *(const f32x4*)(g_v + d), v1 = g[bj][1] * rs * *(const f32x4*)(g_v + d + 4);
;                 st_bf16x8(pV + (size_t)row * 512 + d, v0, v1);
;                 if (row >= NP && row < NTOK) { float* o = out + O_VS + (size_t)(row - NP) * 512 + d; *(f32x4*)o = v0; *(f32x4*)(o + 4) = v1; } }
.LBB0_295:
	s_andn2_b64 vcc, exec, s[0:1]
	s_cbranch_vccnz .LBB0_301
	v_mov_b32_e32 v190, 0x3d372713
	v_mov_b32_e32 v192, 0xbfcc422a
	v_mov_b32_e32 v194, 0x3fb8aa3b
	v_pk_mul_f32 v[64:65], v[60:61], v[190:191] op_sel_hi:[1,0]
	v_pk_mul_f32 v[68:69], v[62:63], v[190:191] op_sel_hi:[1,0]
	v_pk_mul_f32 v[74:75], v[56:57], v[190:191] op_sel_hi:[1,0]
	v_pk_mul_f32 v[76:77], v[58:59], v[190:191] op_sel_hi:[1,0]
	v_pk_mul_f32 v[78:79], v[52:53], v[190:191] op_sel_hi:[1,0]
	v_pk_mul_f32 v[80:81], v[54:55], v[190:191] op_sel_hi:[1,0]
	v_pk_mul_f32 v[82:83], v[48:49], v[190:191] op_sel_hi:[1,0]
	v_pk_mul_f32 v[84:85], v[50:51], v[190:191] op_sel_hi:[1,0]
	v_pk_mul_f32 v[64:65], v[60:61], v[64:65]
	v_pk_mul_f32 v[68:69], v[62:63], v[68:69]
	v_pk_mul_f32 v[74:75], v[56:57], v[74:75]
	v_pk_mul_f32 v[76:77], v[58:59], v[76:77]
	v_pk_mul_f32 v[78:79], v[52:53], v[78:79]
	v_pk_mul_f32 v[80:81], v[54:55], v[80:81]
	v_pk_mul_f32 v[82:83], v[48:49], v[82:83]
	v_pk_mul_f32 v[84:85], v[50:51], v[84:85]
	v_pk_fma_f32 v[64:65], v[60:61], v[64:65], v[60:61]
	v_pk_fma_f32 v[68:69], v[62:63], v[68:69], v[62:63]
	v_pk_fma_f32 v[74:75], v[56:57], v[74:75], v[56:57]
	v_pk_fma_f32 v[76:77], v[58:59], v[76:77], v[58:59]
	v_pk_fma_f32 v[78:79], v[52:53], v[78:79], v[52:53]
	v_pk_fma_f32 v[80:81], v[54:55], v[80:81], v[54:55]
	v_pk_fma_f32 v[82:83], v[48:49], v[82:83], v[48:49]
	v_pk_fma_f32 v[84:85], v[50:51], v[84:85], v[50:51]
	v_pk_mul_f32 v[64:65], v[64:65], v[192:193] op_sel_hi:[1,0]
	v_pk_mul_f32 v[68:69], v[68:69], v[192:193] op_sel_hi:[1,0]
	v_pk_mul_f32 v[74:75], v[74:75], v[192:193] op_sel_hi:[1,0]
	v_pk_mul_f32 v[76:77], v[76:77], v[192:193] op_sel_hi:[1,0]
	v_pk_mul_f32 v[78:79], v[78:79], v[192:193] op_sel_hi:[1,0]
	v_pk_mul_f32 v[80:81], v[80:81], v[192:193] op_sel_hi:[1,0]
	v_pk_mul_f32 v[82:83], v[82:83], v[192:193] op_sel_hi:[1,0]
	v_pk_mul_f32 v[84:85], v[84:85], v[192:193] op_sel_hi:[1,0]
	v_pk_mul_f32 v[64:65], v[64:65], v[194:195] op_sel_hi:[1,0]
	v_pk_mul_f32 v[68:69], v[68:69], v[194:195] op_sel_hi:[1,0]
	v_pk_mul_f32 v[74:75], v[74:75], v[194:195] op_sel_hi:[1,0]
	v_pk_mul_f32 v[76:77], v[76:77], v[194:195] op_sel_hi:[1,0]
	v_pk_mul_f32 v[78:79], v[78:79], v[194:195] op_sel_hi:[1,0]
	v_pk_mul_f32 v[80:81], v[80:81], v[194:195] op_sel_hi:[1,0]
	v_pk_mul_f32 v[82:83], v[82:83], v[194:195] op_sel_hi:[1,0]
	v_pk_mul_f32 v[84:85], v[84:85], v[194:195] op_sel_hi:[1,0]
	v_exp_f32_e32 v64, v64
	v_exp_f32_e32 v65, v65
	v_exp_f32_e32 v68, v68
	v_exp_f32_e32 v69, v69
	v_exp_f32_e32 v74, v74
	v_exp_f32_e32 v75, v75
	v_exp_f32_e32 v76, v76
	v_exp_f32_e32 v77, v77
	v_exp_f32_e32 v78, v78
	v_exp_f32_e32 v79, v79
	v_exp_f32_e32 v80, v80
	v_exp_f32_e32 v81, v81
	v_exp_f32_e32 v82, v82
	v_exp_f32_e32 v83, v83
	v_exp_f32_e32 v84, v84
	v_exp_f32_e32 v85, v85
	v_pk_add_f32 v[64:65], v[64:65], 1.0 op_sel_hi:[1,0]
	v_pk_add_f32 v[68:69], v[68:69], 1.0 op_sel_hi:[1,0]
	v_pk_add_f32 v[74:75], v[74:75], 1.0 op_sel_hi:[1,0]
	v_pk_add_f32 v[76:77], v[76:77], 1.0 op_sel_hi:[1,0]
	v_pk_add_f32 v[78:79], v[78:79], 1.0 op_sel_hi:[1,0]
	v_pk_add_f32 v[80:81], v[80:81], 1.0 op_sel_hi:[1,0]
	v_pk_add_f32 v[82:83], v[82:83], 1.0 op_sel_hi:[1,0]
	v_pk_add_f32 v[84:85], v[84:85], 1.0 op_sel_hi:[1,0]
	v_rcp_f32_e32 v64, v64
	v_rcp_f32_e32 v65, v65
	v_rcp_f32_e32 v68, v68
	v_rcp_f32_e32 v69, v69
	v_rcp_f32_e32 v74, v74
	v_rcp_f32_e32 v75, v75
	v_rcp_f32_e32 v76, v76
	v_rcp_f32_e32 v77, v77
	v_rcp_f32_e32 v78, v78
	v_rcp_f32_e32 v79, v79
	v_rcp_f32_e32 v80, v80
	v_rcp_f32_e32 v81, v81
	v_rcp_f32_e32 v82, v82
	v_rcp_f32_e32 v83, v83
	v_rcp_f32_e32 v84, v84
	v_rcp_f32_e32 v85, v85
	v_pk_mul_f32 v[64:65], v[60:61], v[64:65]
	v_pk_mul_f32 v[68:69], v[62:63], v[68:69]
	v_pk_mul_f32 v[74:75], v[56:57], v[74:75]
	v_pk_mul_f32 v[76:77], v[58:59], v[76:77]
	v_pk_mul_f32 v[78:79], v[52:53], v[78:79]
	v_pk_mul_f32 v[80:81], v[54:55], v[80:81]
	v_pk_mul_f32 v[82:83], v[48:49], v[82:83]
	v_pk_mul_f32 v[84:85], v[50:51], v[84:85]
	v_pk_mul_f32 v[66:67], v[64:65], v[64:65]
	v_pk_mul_f32 v[70:71], v[68:69], v[68:69]
	v_add_f32_e32 v66, v66, v67
	v_add_f32_e32 v66, v70, v66
	v_pk_mul_f32 v[86:87], v[74:75], v[74:75]
	v_add_f32_e32 v66, v71, v66
	v_add_f32_e32 v66, v86, v66
	v_pk_mul_f32 v[88:89], v[76:77], v[76:77]
	v_add_f32_e32 v66, v87, v66
	v_add_f32_e32 v66, v88, v66
	v_pk_mul_f32 v[90:91], v[78:79], v[78:79]
	v_add_f32_e32 v66, v89, v66
	v_add_f32_e32 v66, v66, v90
	v_pk_mul_f32 v[92:93], v[80:81], v[80:81]
	v_add_f32_e32 v66, v91, v66
	v_add_f32_e32 v66, v92, v66
	v_pk_mul_f32 v[94:95], v[82:83], v[82:83]
	v_add_f32_e32 v66, v93, v66
	v_add_f32_e32 v66, v94, v66
	v_pk_mul_f32 v[96:97], v[84:85], v[84:85]
	v_add_f32_e32 v66, v95, v66
	v_add_f32_e32 v66, v96, v66
	v_add_f32_e32 v66, v97, v66
	v_mov_b32_e32 v67, v66
	s_nop 1
	v_permlane16_swap_b32 v66, v67
	v_lshl_add_u64 v[96:97], v[140:141], 2, s[18:19]
	v_ashrrev_i32_e32 v73, 31, v72
	v_lshlrev_b64 v[90:91], 10, v[72:73]
	v_lshlrev_b32_e32 v88, 9, v72
	s_waitcnt lgkmcnt(0)
	v_add_f32_e32 v66, v66, v67
	v_mov_b32_e32 v67, v66
	s_nop 1
	v_permlane32_swap_b32 v66, v67
	v_mov_b32_e32 v89, v141
	s_waitcnt lgkmcnt(0)
	v_add_f32_e32 v66, v66, v67
	v_fmamk_f32 v66, v66, 0x3c800000, v188
	v_cmp_gt_f32_e32 vcc, s13, v66
	v_mul_f32_e32 v67, 0x4b800000, v66
	s_nop 0
	v_cndmask_b32_e32 v66, v66, v67, vcc
	v_rsq_f32_e32 v66, v66
	s_nop 0
	v_mul_f32_e32 v67, 0x45800000, v66
	v_cndmask_b32_e32 v86, v66, v67, vcc
	v_pk_mul_f32 v[92:93], v[64:65], v[86:87] op_sel_hi:[1,0]
	v_pk_mul_f32 v[94:95], v[68:69], v[86:87] op_sel_hi:[1,0]
	v_mov_b64_e32 v[64:65], v[208:209]
	v_mov_b64_e32 v[66:67], v[210:211]
	v_mov_b64_e32 v[68:69], v[204:205]
	v_mov_b64_e32 v[70:71], v[206:207]
	v_pk_mul_f32 v[74:75], v[74:75], v[86:87] op_sel_hi:[1,0]
	v_pk_mul_f32 v[76:77], v[76:77], v[86:87] op_sel_hi:[1,0]
	v_pk_mul_f32 v[64:65], v[64:65], v[74:75]
	v_lshl_add_u64 v[74:75], s[46:47], 0, v[90:91]
	v_pk_mul_f32 v[70:71], v[70:71], v[94:95]
	v_pk_mul_f32 v[68:69], v[68:69], v[92:93]
	v_pk_mul_f32 v[66:67], v[66:67], v[76:77]
	v_lshl_add_u64 v[76:77], v[140:141], 1, v[74:75]
	v_lshl_add_u64 v[74:75], v[88:89], 2, s[56:57]
	v_cvt_pk_bf16_f32 v90, v68, v69
	v_cvt_pk_bf16_f32 v91, v70, v71
	v_cvt_pk_bf16_f32 v92, v64, v65
	v_cvt_pk_bf16_f32 v93, v66, v67
	global_store_dwordx4 v[76:77], v[90:93], off
	s_and_saveexec_b64 s[0:1], s[10:11]
	s_cbranch_execz .LBB0_298
	v_lshl_add_u64 v[88:89], v[140:141], 2, v[74:75]
	v_lshl_add_u64 v[90:91], v[88:89], 0, s[70:71]
	v_add_co_u32_e32 v88, vcc, 0x2108000, v88
	s_nop 1
	v_addc_co_u32_e32 v89, vcc, 0, v89, vcc
	global_store_dwordx4 v[88:89], v[68:71], off
	global_store_dwordx4 v[90:91], v[64:67], off offset:16

; __device__ __forceinline__ float gelu_tanh(float x) { const float u = 1.5957691216f * (x + 0.044715f * x * x * x); return x * __builtin_amdgcn_rcpf(1.f + __expf(-u)); }
; __device__ __forceinline__ void st_bf16x8(bf16_t* p, const f32x4 a, const f32x4 b) { uint4 o; o.x = cvt_pk_bf16(a[0], a[1]); o.y = cvt_pk_bf16(a[2], a[3]); o.z = cvt_pk_bf16(b[0], b[1]); o.w = cvt_pk_bf16(b[2], b[3]); *(uint4*)p = o; }
;     __device__ __forceinline__ void row(const f32x4 (&a)[2][2], int row, int pn, int wc, int fq) const {
;     ...
;         } else if (pn < 4) {
;             const int head = (pn - 2) * 4 + wc;
;             f32x4 g[2][2]; float ss = 0.f;
; #pragma unroll
;             for (int bj = 0; bj < 2; ++bj)
; #pragma unroll
;                 for (int n = 0; n < 2; ++n)
; #pragma unroll
;                     for (int j = 0; j < 4; ++j) { const float t = gelu_tanh(a[bj][n][j]); g[bj][n][j] = t; ss += t * t; }
;             ss += __shfl_xor(ss, 16); ss += __shfl_xor(ss, 32);
;             const float rs = rsqrtf(ss * (1.f / 64.f) + EPS);
; #pragma unroll
;             for (int bj = 0; bj < 2; ++bj) { const int d = head * 64 + bj * 32 + 8 * fq;
;                 const f32x4 v0 = g[bj][0] * rs * *(const f32x4*)(g_v + d), v1 = g[bj][1] * rs * *(const f32x4*)(g_v + d + 4);
;                 st_bf16x8(pV + (size_t)row * 512 + d, v0, v1);
;                 if (row >= NP && row < NTOK) { float* o = out + O_VS + (size_t)(row - NP) * 512 + d; *(f32x4*)o = v0; *(f32x4*)(o + 4) = v1; } }
.LBB0_311:
	s_andn2_b64 vcc, exec, s[0:1]
	s_cbranch_vccnz .LBB0_317
	v_mov_b32_e32 v190, 0x3d372713
	v_mov_b32_e32 v192, 0xbfcc422a
	v_mov_b32_e32 v194, 0x3fb8aa3b
	v_pk_mul_f32 v[48:49], v[44:45], v[190:191] op_sel_hi:[1,0]
	v_pk_mul_f32 v[52:53], v[46:47], v[190:191] op_sel_hi:[1,0]
	v_pk_mul_f32 v[58:59], v[40:41], v[190:191] op_sel_hi:[1,0]
	v_pk_mul_f32 v[60:61], v[42:43], v[190:191] op_sel_hi:[1,0]
	v_pk_mul_f32 v[62:63], v[36:37], v[190:191] op_sel_hi:[1,0]
	v_pk_mul_f32 v[64:65], v[38:39], v[190:191] op_sel_hi:[1,0]
	v_pk_mul_f32 v[66:67], v[32:33], v[190:191] op_sel_hi:[1,0]
	v_pk_mul_f32 v[68:69], v[34:35], v[190:191] op_sel_hi:[1,0]
	v_pk_mul_f32 v[48:49], v[44:45], v[48:49]
	v_pk_mul_f32 v[52:53], v[46:47], v[52:53]
	v_pk_mul_f32 v[58:59], v[40:41], v[58:59]
	v_pk_mul_f32 v[60:61], v[42:43], v[60:61]
	v_pk_mul_f32 v[62:63], v[36:37], v[62:63]
	v_pk_mul_f32 v[64:65], v[38:39], v[64:65]
	v_pk_mul_f32 v[66:67], v[32:33], v[66:67]
	v_pk_mul_f32 v[68:69], v[34:35], v[68:69]
	v_pk_fma_f32 v[48:49], v[44:45], v[48:49], v[44:45]
	v_pk_fma_f32 v[52:53], v[46:47], v[52:53], v[46:47]
	v_pk_fma_f32 v[58:59], v[40:41], v[58:59], v[40:41]
	v_pk_fma_f32 v[60:61], v[42:43], v[60:61], v[42:43]
	v_pk_fma_f32 v[62:63], v[36:37], v[62:63], v[36:37]
	v_pk_fma_f32 v[64:65], v[38:39], v[64:65], v[38:39]
	v_pk_fma_f32 v[66:67], v[32:33], v[66:67], v[32:33]
	v_pk_fma_f32 v[68:69], v[34:35], v[68:69], v[34:35]
	v_pk_mul_f32 v[48:49], v[48:49], v[192:193] op_sel_hi:[1,0]
	v_pk_mul_f32 v[52:53], v[52:53], v[192:193] op_sel_hi:[1,0]
	v_pk_mul_f32 v[58:59], v[58:59], v[192:193] op_sel_hi:[1,0]
	v_pk_mul_f32 v[60:61], v[60:61], v[192:193] op_sel_hi:[1,0]
	v_pk_mul_f32 v[62:63], v[62:63], v[192:193] op_sel_hi:[1,0]
	v_pk_mul_f32 v[64:65], v[64:65], v[192:193] op_sel_hi:[1,0]
	v_pk_mul_f32 v[66:67], v[66:67], v[192:193] op_sel_hi:[1,0]
	v_pk_mul_f32 v[68:69], v[68:69], v[192:193] op_sel_hi:[1,0]
	v_pk_mul_f32 v[48:49], v[48:49], v[194:195] op_sel_hi:[1,0]
	v_pk_mul_f32 v[52:53], v[52:53], v[194:195] op_sel_hi:[1,0]
	v_pk_mul_f32 v[58:59], v[58:59], v[194:195] op_sel_hi:[1,0]
	v_pk_mul_f32 v[60:61], v[60:61], v[194:195] op_sel_hi:[1,0]
	v_pk_mul_f32 v[62:63], v[62:63], v[194:195] op_sel_hi:[1,0]
	v_pk_mul_f32 v[64:65], v[64:65], v[194:195] op_sel_hi:[1,0]
	v_pk_mul_f32 v[66:67], v[66:67], v[194:195] op_sel_hi:[1,0]
	v_pk_mul_f32 v[68:69], v[68:69], v[194:195] op_sel_hi:[1,0]
	v_exp_f32_e32 v48, v48
	v_exp_f32_e32 v49, v49
	v_exp_f32_e32 v52, v52
	v_exp_f32_e32 v53, v53
	v_exp_f32_e32 v58, v58
	v_exp_f32_e32 v59, v59
	v_exp_f32_e32 v60, v60
	v_exp_f32_e32 v61, v61
	v_exp_f32_e32 v62, v62
	v_exp_f32_e32 v63, v63
	v_exp_f32_e32 v64, v64
	v_exp_f32_e32 v65, v65
	v_exp_f32_e32 v66, v66
	v_exp_f32_e32 v67, v67
	v_exp_f32_e32 v68, v68
	v_exp_f32_e32 v69, v69
	v_pk_add_f32 v[48:49], v[48:49], 1.0 op_sel_hi:[1,0]
	v_pk_add_f32 v[52:53], v[52:53], 1.0 op_sel_hi:[1,0]
	v_pk_add_f32 v[58:59], v[58:59], 1.0 op_sel_hi:[1,0]
	v_pk_add_f32 v[60:61], v[60:61], 1.0 op_sel_hi:[1,0]
	v_pk_add_f32 v[62:63], v[62:63], 1.0 op_sel_hi:[1,0]
	v_pk_add_f32 v[64:65], v[64:65], 1.0 op_sel_hi:[1,0]
	v_pk_add_f32 v[66:67], v[66:67], 1.0 op_sel_hi:[1,0]
	v_pk_add_f32 v[68:69], v[68:69], 1.0 op_sel_hi:[1,0]
	v_rcp_f32_e32 v48, v48
	v_rcp_f32_e32 v49, v49
	v_rcp_f32_e32 v52, v52
	v_rcp_f32_e32 v53, v53
	v_rcp_f32_e32 v58, v58
	v_rcp_f32_e32 v59, v59
	v_rcp_f32_e32 v60, v60
	v_rcp_f32_e32 v61, v61
	v_rcp_f32_e32 v62, v62
	v_rcp_f32_e32 v63, v63
	v_rcp_f32_e32 v64, v64
	v_rcp_f32_e32 v65, v65
	v_rcp_f32_e32 v66, v66
	v_rcp_f32_e32 v67, v67
	v_rcp_f32_e32 v68, v68
	v_rcp_f32_e32 v69, v69
	v_pk_mul_f32 v[48:49], v[44:45], v[48:49]
	v_pk_mul_f32 v[52:53], v[46:47], v[52:53]
	v_pk_mul_f32 v[58:59], v[40:41], v[58:59]
	v_pk_mul_f32 v[60:61], v[42:43], v[60:61]
	v_pk_mul_f32 v[62:63], v[36:37], v[62:63]
	v_pk_mul_f32 v[64:65], v[38:39], v[64:65]
	v_pk_mul_f32 v[66:67], v[32:33], v[66:67]
	v_pk_mul_f32 v[68:69], v[34:35], v[68:69]
	v_pk_mul_f32 v[50:51], v[48:49], v[48:49]
	v_pk_mul_f32 v[54:55], v[52:53], v[52:53]
	v_add_f32_e32 v50, v50, v51
	v_add_f32_e32 v50, v54, v50
	v_pk_mul_f32 v[70:71], v[58:59], v[58:59]
	v_add_f32_e32 v50, v55, v50
	v_add_f32_e32 v50, v70, v50
	v_pk_mul_f32 v[74:75], v[60:61], v[60:61]
	v_add_f32_e32 v50, v71, v50
	v_add_f32_e32 v50, v74, v50
	v_pk_mul_f32 v[76:77], v[62:63], v[62:63]
	v_add_f32_e32 v50, v75, v50
	v_add_f32_e32 v50, v50, v76
	v_pk_mul_f32 v[78:79], v[64:65], v[64:65]
	v_add_f32_e32 v50, v77, v50
	v_add_f32_e32 v50, v78, v50
	v_pk_mul_f32 v[80:81], v[66:67], v[66:67]
	v_add_f32_e32 v50, v79, v50
	v_add_f32_e32 v50, v80, v50
	v_pk_mul_f32 v[82:83], v[68:69], v[68:69]
	v_add_f32_e32 v50, v81, v50
	v_add_f32_e32 v50, v82, v50
	v_add_f32_e32 v50, v83, v50
	v_mov_b32_e32 v51, v50
	s_nop 1
	v_permlane16_swap_b32 v50, v51
	v_lshl_add_u64 v[82:83], v[140:141], 2, s[18:19]
	v_ashrrev_i32_e32 v57, 31, v56
	v_lshlrev_b64 v[76:77], 10, v[56:57]
	v_lshlrev_b32_e32 v74, 9, v56
	s_waitcnt lgkmcnt(0)
	v_add_f32_e32 v50, v50, v51
	v_mov_b32_e32 v51, v50
	s_nop 1
	v_permlane32_swap_b32 v50, v51
	v_mov_b32_e32 v75, v141
	s_waitcnt lgkmcnt(0)
	v_add_f32_e32 v50, v50, v51
	v_fmamk_f32 v50, v50, 0x3c800000, v188
	v_cmp_gt_f32_e32 vcc, s13, v50
	v_mul_f32_e32 v51, 0x4b800000, v50
	s_nop 0
	v_cndmask_b32_e32 v50, v50, v51, vcc
	v_rsq_f32_e32 v50, v50
	s_nop 0
	v_mul_f32_e32 v51, 0x45800000, v50
	v_cndmask_b32_e32 v70, v50, v51, vcc
	v_pk_mul_f32 v[78:79], v[48:49], v[70:71] op_sel_hi:[1,0]
	v_pk_mul_f32 v[80:81], v[52:53], v[70:71] op_sel_hi:[1,0]
	v_mov_b64_e32 v[48:49], v[208:209]
	v_mov_b64_e32 v[50:51], v[210:211]
	v_mov_b64_e32 v[52:53], v[204:205]
	v_mov_b64_e32 v[54:55], v[206:207]
	v_pk_mul_f32 v[58:59], v[58:59], v[70:71] op_sel_hi:[1,0]
	v_pk_mul_f32 v[60:61], v[60:61], v[70:71] op_sel_hi:[1,0]
	v_pk_mul_f32 v[48:49], v[48:49], v[58:59]
	v_lshl_add_u64 v[58:59], s[46:47], 0, v[76:77]
	v_pk_mul_f32 v[54:55], v[54:55], v[80:81]
	v_pk_mul_f32 v[52:53], v[52:53], v[78:79]
	v_pk_mul_f32 v[50:51], v[50:51], v[60:61]
	v_lshl_add_u64 v[60:61], v[140:141], 1, v[58:59]
	v_lshl_add_u64 v[58:59], v[74:75], 2, s[56:57]
	v_cvt_pk_bf16_f32 v76, v52, v53
	v_cvt_pk_bf16_f32 v77, v54, v55
	v_cvt_pk_bf16_f32 v78, v48, v49
	v_cvt_pk_bf16_f32 v79, v50, v51
	global_store_dwordx4 v[60:61], v[76:79], off
	s_and_saveexec_b64 s[0:1], s[10:11]
	s_cbranch_execz .LBB0_314
	v_lshl_add_u64 v[74:75], v[140:141], 2, v[58:59]
	v_lshl_add_u64 v[76:77], v[74:75], 0, s[70:71]
	v_add_co_u32_e32 v74, vcc, 0x2108000, v74
	s_nop 1
	v_addc_co_u32_e32 v75, vcc, 0, v75, vcc
	global_store_dwordx4 v[74:75], v[52:55], off
	global_store_dwordx4 v[76:77], v[48:51], off offset:16

; __device__ __forceinline__ float gelu_tanh(float x) { const float u = 1.5957691216f * (x + 0.044715f * x * x * x); return x * __builtin_amdgcn_rcpf(1.f + __expf(-u)); }
; __device__ __forceinline__ void st_bf16x8(bf16_t* p, const f32x4 a, const f32x4 b) { uint4 o; o.x = cvt_pk_bf16(a[0], a[1]); o.y = cvt_pk_bf16(a[2], a[3]); o.z = cvt_pk_bf16(b[0], b[1]); o.w = cvt_pk_bf16(b[2], b[3]); *(uint4*)p = o; }
;     __device__ __forceinline__ void row(const f32x4 (&a)[2][2], int row, int pn, int wc, int fq) const {
;     ...
;         } else if (pn < 4) {
;             const int head = (pn - 2) * 4 + wc;
;             f32x4 g[2][2]; float ss = 0.f;
; #pragma unroll
;             for (int bj = 0; bj < 2; ++bj)
; #pragma unroll
;                 for (int n = 0; n < 2; ++n)
; #pragma unroll
;                     for (int j = 0; j < 4; ++j) { const float t = gelu_tanh(a[bj][n][j]); g[bj][n][j] = t; ss += t * t; }
;             ss += __shfl_xor(ss, 16); ss += __shfl_xor(ss, 32);
;             const float rs = rsqrtf(ss * (1.f / 64.f) + EPS);
; #pragma unroll
;             for (int bj = 0; bj < 2; ++bj) { const int d = head * 64 + bj * 32 + 8 * fq;
;                 const f32x4 v0 = g[bj][0] * rs * *(const f32x4*)(g_v + d), v1 = g[bj][1] * rs * *(const f32x4*)(g_v + d + 4);
;                 st_bf16x8(pV + (size_t)row * 512 + d, v0, v1);
;                 if (row >= NP && row < NTOK) { float* o = out + O_VS + (size_t)(row - NP) * 512 + d; *(f32x4*)o = v0; *(f32x4*)(o + 4) = v1; } }
.LBB0_327:
	s_andn2_b64 vcc, exec, s[0:1]
	s_cbranch_vccnz .LBB0_333
	v_mov_b32_e32 v190, 0x3d372713
	v_mov_b32_e32 v192, 0xbfcc422a
	v_mov_b32_e32 v194, 0x3fb8aa3b
	v_pk_mul_f32 v[32:33], v[28:29], v[190:191] op_sel_hi:[1,0]
	v_pk_mul_f32 v[36:37], v[30:31], v[190:191] op_sel_hi:[1,0]
	v_pk_mul_f32 v[42:43], v[24:25], v[190:191] op_sel_hi:[1,0]
	v_pk_mul_f32 v[44:45], v[26:27], v[190:191] op_sel_hi:[1,0]
	v_pk_mul_f32 v[46:47], v[20:21], v[190:191] op_sel_hi:[1,0]
	v_pk_mul_f32 v[48:49], v[22:23], v[190:191] op_sel_hi:[1,0]
	v_pk_mul_f32 v[50:51], v[16:17], v[190:191] op_sel_hi:[1,0]
	v_pk_mul_f32 v[52:53], v[18:19], v[190:191] op_sel_hi:[1,0]
	v_pk_mul_f32 v[32:33], v[28:29], v[32:33]
	v_pk_mul_f32 v[36:37], v[30:31], v[36:37]
	v_pk_mul_f32 v[42:43], v[24:25], v[42:43]
	v_pk_mul_f32 v[44:45], v[26:27], v[44:45]
	v_pk_mul_f32 v[46:47], v[20:21], v[46:47]
	v_pk_mul_f32 v[48:49], v[22:23], v[48:49]
	v_pk_mul_f32 v[50:51], v[16:17], v[50:51]
	v_pk_mul_f32 v[52:53], v[18:19], v[52:53]
	v_pk_fma_f32 v[32:33], v[28:29], v[32:33], v[28:29]
	v_pk_fma_f32 v[36:37], v[30:31], v[36:37], v[30:31]
	v_pk_fma_f32 v[42:43], v[24:25], v[42:43], v[24:25]
	v_pk_fma_f32 v[44:45], v[26:27], v[44:45], v[26:27]
	v_pk_fma_f32 v[46:47], v[20:21], v[46:47], v[20:21]
	v_pk_fma_f32 v[48:49], v[22:23], v[48:49], v[22:23]
	v_pk_fma_f32 v[50:51], v[16:17], v[50:51], v[16:17]
	v_pk_fma_f32 v[52:53], v[18:19], v[52:53], v[18:19]
	v_pk_mul_f32 v[32:33], v[32:33], v[192:193] op_sel_hi:[1,0]
	v_pk_mul_f32 v[36:37], v[36:37], v[192:193] op_sel_hi:[1,0]
	v_pk_mul_f32 v[42:43], v[42:43], v[192:193] op_sel_hi:[1,0]
	v_pk_mul_f32 v[44:45], v[44:45], v[192:193] op_sel_hi:[1,0]
	v_pk_mul_f32 v[46:47], v[46:47], v[192:193] op_sel_hi:[1,0]
	v_pk_mul_f32 v[48:49], v[48:49], v[192:193] op_sel_hi:[1,0]
	v_pk_mul_f32 v[50:51], v[50:51], v[192:193] op_sel_hi:[1,0]
	v_pk_mul_f32 v[52:53], v[52:53], v[192:193] op_sel_hi:[1,0]
	v_pk_mul_f32 v[32:33], v[32:33], v[194:195] op_sel_hi:[1,0]
	v_pk_mul_f32 v[36:37], v[36:37], v[194:195] op_sel_hi:[1,0]
	v_pk_mul_f32 v[42:43], v[42:43], v[194:195] op_sel_hi:[1,0]
	v_pk_mul_f32 v[44:45], v[44:45], v[194:195] op_sel_hi:[1,0]
	v_pk_mul_f32 v[46:47], v[46:47], v[194:195] op_sel_hi:[1,0]
	v_pk_mul_f32 v[48:49], v[48:49], v[194:195] op_sel_hi:[1,0]
	v_pk_mul_f32 v[50:51], v[50:51], v[194:195] op_sel_hi:[1,0]
	v_pk_mul_f32 v[52:53], v[52:53], v[194:195] op_sel_hi:[1,0]
	v_exp_f32_e32 v32, v32
	v_exp_f32_e32 v33, v33
	v_exp_f32_e32 v36, v36
	v_exp_f32_e32 v37, v37
	v_exp_f32_e32 v42, v42
	v_exp_f32_e32 v43, v43
	v_exp_f32_e32 v44, v44
	v_exp_f32_e32 v45, v45
	v_exp_f32_e32 v46, v46
	v_exp_f32_e32 v47, v47
	v_exp_f32_e32 v48, v48
	v_exp_f32_e32 v49, v49
	v_exp_f32_e32 v50, v50
	v_exp_f32_e32 v51, v51
	v_exp_f32_e32 v52, v52
	v_exp_f32_e32 v53, v53
	v_pk_add_f32 v[32:33], v[32:33], 1.0 op_sel_hi:[1,0]
	v_pk_add_f32 v[36:37], v[36:37], 1.0 op_sel_hi:[1,0]
	v_pk_add_f32 v[42:43], v[42:43], 1.0 op_sel_hi:[1,0]
	v_pk_add_f32 v[44:45], v[44:45], 1.0 op_sel_hi:[1,0]
	v_pk_add_f32 v[46:47], v[46:47], 1.0 op_sel_hi:[1,0]
	v_pk_add_f32 v[48:49], v[48:49], 1.0 op_sel_hi:[1,0]
	v_pk_add_f32 v[50:51], v[50:51], 1.0 op_sel_hi:[1,0]
	v_pk_add_f32 v[52:53], v[52:53], 1.0 op_sel_hi:[1,0]
	v_rcp_f32_e32 v32, v32
	v_rcp_f32_e32 v33, v33
	v_rcp_f32_e32 v36, v36
	v_rcp_f32_e32 v37, v37
	v_rcp_f32_e32 v42, v42
	v_rcp_f32_e32 v43, v43
	v_rcp_f32_e32 v44, v44
	v_rcp_f32_e32 v45, v45
	v_rcp_f32_e32 v46, v46
	v_rcp_f32_e32 v47, v47
	v_rcp_f32_e32 v48, v48
	v_rcp_f32_e32 v49, v49
	v_rcp_f32_e32 v50, v50
	v_rcp_f32_e32 v51, v51
	v_rcp_f32_e32 v52, v52
	v_rcp_f32_e32 v53, v53
	v_pk_mul_f32 v[32:33], v[28:29], v[32:33]
	v_pk_mul_f32 v[36:37], v[30:31], v[36:37]
	v_pk_mul_f32 v[42:43], v[24:25], v[42:43]
	v_pk_mul_f32 v[44:45], v[26:27], v[44:45]
	v_pk_mul_f32 v[46:47], v[20:21], v[46:47]
	v_pk_mul_f32 v[48:49], v[22:23], v[48:49]
	v_pk_mul_f32 v[50:51], v[16:17], v[50:51]
	v_pk_mul_f32 v[52:53], v[18:19], v[52:53]
	v_pk_mul_f32 v[34:35], v[32:33], v[32:33]
	v_pk_mul_f32 v[38:39], v[36:37], v[36:37]
	v_add_f32_e32 v34, v34, v35
	v_add_f32_e32 v34, v38, v34
	v_pk_mul_f32 v[54:55], v[42:43], v[42:43]
	v_add_f32_e32 v34, v39, v34
	v_add_f32_e32 v34, v54, v34
	v_pk_mul_f32 v[56:57], v[44:45], v[44:45]
	v_add_f32_e32 v34, v55, v34
	v_add_f32_e32 v34, v56, v34
	v_pk_mul_f32 v[58:59], v[46:47], v[46:47]
	v_add_f32_e32 v34, v57, v34
	v_add_f32_e32 v34, v34, v58
	v_pk_mul_f32 v[60:61], v[48:49], v[48:49]
	v_add_f32_e32 v34, v59, v34
	v_add_f32_e32 v34, v60, v34
	v_pk_mul_f32 v[62:63], v[50:51], v[50:51]
	v_add_f32_e32 v34, v61, v34
	v_add_f32_e32 v34, v62, v34
	v_pk_mul_f32 v[64:65], v[52:53], v[52:53]
	v_add_f32_e32 v34, v63, v34
	v_add_f32_e32 v34, v64, v34
	v_add_f32_e32 v34, v65, v34
	v_mov_b32_e32 v35, v34
	s_nop 1
	v_permlane16_swap_b32 v34, v35
	v_lshl_add_u64 v[64:65], v[140:141], 2, s[18:19]
	v_ashrrev_i32_e32 v41, 31, v40
	v_lshlrev_b64 v[58:59], 10, v[40:41]
	v_lshlrev_b32_e32 v56, 9, v40
	s_waitcnt lgkmcnt(0)
	v_add_f32_e32 v34, v34, v35
	v_mov_b32_e32 v35, v34
	s_nop 1
	v_permlane32_swap_b32 v34, v35
	v_mov_b32_e32 v57, v141
	s_waitcnt lgkmcnt(0)
	v_add_f32_e32 v34, v34, v35
	v_fmamk_f32 v34, v34, 0x3c800000, v188
	v_cmp_gt_f32_e32 vcc, s13, v34
	v_mul_f32_e32 v35, 0x4b800000, v34
	s_nop 0
	v_cndmask_b32_e32 v34, v34, v35, vcc
	v_rsq_f32_e32 v34, v34
	s_nop 0
	v_mul_f32_e32 v35, 0x45800000, v34
	v_cndmask_b32_e32 v54, v34, v35, vcc
	v_pk_mul_f32 v[60:61], v[32:33], v[54:55] op_sel_hi:[1,0]
	v_pk_mul_f32 v[62:63], v[36:37], v[54:55] op_sel_hi:[1,0]
	v_mov_b64_e32 v[32:33], v[208:209]
	v_mov_b64_e32 v[34:35], v[210:211]
	v_mov_b64_e32 v[36:37], v[204:205]
	v_mov_b64_e32 v[38:39], v[206:207]
	v_pk_mul_f32 v[42:43], v[42:43], v[54:55] op_sel_hi:[1,0]
	v_pk_mul_f32 v[44:45], v[44:45], v[54:55] op_sel_hi:[1,0]
	v_pk_mul_f32 v[32:33], v[32:33], v[42:43]
	v_lshl_add_u64 v[42:43], s[46:47], 0, v[58:59]
	v_pk_mul_f32 v[38:39], v[38:39], v[62:63]
	v_pk_mul_f32 v[36:37], v[36:37], v[60:61]
	v_pk_mul_f32 v[34:35], v[34:35], v[44:45]
	v_lshl_add_u64 v[44:45], v[140:141], 1, v[42:43]
	v_lshl_add_u64 v[42:43], v[56:57], 2, s[56:57]
	v_cvt_pk_bf16_f32 v58, v36, v37
	v_cvt_pk_bf16_f32 v59, v38, v39
	v_cvt_pk_bf16_f32 v60, v32, v33
	v_cvt_pk_bf16_f32 v61, v34, v35
	global_store_dwordx4 v[44:45], v[58:61], off
	s_and_saveexec_b64 s[0:1], s[10:11]
	s_cbranch_execz .LBB0_330
	v_lshl_add_u64 v[56:57], v[140:141], 2, v[42:43]
	v_lshl_add_u64 v[58:59], v[56:57], 0, s[70:71]
	v_add_co_u32_e32 v56, vcc, 0x2108000, v56
	s_nop 1
	v_addc_co_u32_e32 v57, vcc, 0, v57, vcc
	global_store_dwordx4 v[56:57], v[36:39], off
	global_store_dwordx4 v[58:59], v[32:35], off offset:16

; __device__ __forceinline__ float gelu_tanh(float x) { const float u = 1.5957691216f * (x + 0.044715f * x * x * x); return x * __builtin_amdgcn_rcpf(1.f + __expf(-u)); }
; __device__ __forceinline__ void st_bf16x8(bf16_t* p, const f32x4 a, const f32x4 b) { uint4 o; o.x = cvt_pk_bf16(a[0], a[1]); o.y = cvt_pk_bf16(a[2], a[3]); o.z = cvt_pk_bf16(b[0], b[1]); o.w = cvt_pk_bf16(b[2], b[3]); *(uint4*)p = o; }
;     __device__ __forceinline__ void row(const f32x4 (&a)[2][2], int row, int pn, int wc, int fq) const {
;     ...
;         } else if (pn < 4) {
;             const int head = (pn - 2) * 4 + wc;
;             f32x4 g[2][2]; float ss = 0.f;
; #pragma unroll
;             for (int bj = 0; bj < 2; ++bj)
; #pragma unroll
;                 for (int n = 0; n < 2; ++n)
; #pragma unroll
;                     for (int j = 0; j < 4; ++j) { const float t = gelu_tanh(a[bj][n][j]); g[bj][n][j] = t; ss += t * t; }
;             ss += __shfl_xor(ss, 16); ss += __shfl_xor(ss, 32);
;             const float rs = rsqrtf(ss * (1.f / 64.f) + EPS);
; #pragma unroll
;             for (int bj = 0; bj < 2; ++bj) { const int d = head * 64 + bj * 32 + 8 * fq;
;                 const f32x4 v0 = g[bj][0] * rs * *(const f32x4*)(g_v + d), v1 = g[bj][1] * rs * *(const f32x4*)(g_v + d + 4);
;                 st_bf16x8(pV + (size_t)row * 512 + d, v0, v1);
;                 if (row >= NP && row < NTOK) { float* o = out + O_VS + (size_t)(row - NP) * 512 + d; *(f32x4*)o = v0; *(f32x4*)(o + 4) = v1; } }
.LBB0_345:
	s_and_b64 vcc, exec, s[0:1]
	s_cbranch_vccz .LBB0_351
	v_mov_b32_e32 v190, 0x3d372713
	v_mov_b32_e32 v192, 0xbfcc422a
	v_mov_b32_e32 v194, 0x3fb8aa3b
	v_pk_mul_f32 v[16:17], v[12:13], v[190:191] op_sel_hi:[1,0]
	v_pk_mul_f32 v[20:21], v[14:15], v[190:191] op_sel_hi:[1,0]
	v_pk_mul_f32 v[26:27], v[8:9], v[190:191] op_sel_hi:[1,0]
	v_pk_mul_f32 v[28:29], v[10:11], v[190:191] op_sel_hi:[1,0]
	v_pk_mul_f32 v[30:31], v[4:5], v[190:191] op_sel_hi:[1,0]
	v_pk_mul_f32 v[32:33], v[6:7], v[190:191] op_sel_hi:[1,0]
	v_pk_mul_f32 v[34:35], v[0:1], v[190:191] op_sel_hi:[1,0]
	v_pk_mul_f32 v[36:37], v[2:3], v[190:191] op_sel_hi:[1,0]
	v_pk_mul_f32 v[16:17], v[12:13], v[16:17]
	v_pk_mul_f32 v[20:21], v[14:15], v[20:21]
	v_pk_mul_f32 v[26:27], v[8:9], v[26:27]
	v_pk_mul_f32 v[28:29], v[10:11], v[28:29]
	v_pk_mul_f32 v[30:31], v[4:5], v[30:31]
	v_pk_mul_f32 v[32:33], v[6:7], v[32:33]
	v_pk_mul_f32 v[34:35], v[0:1], v[34:35]
	v_pk_mul_f32 v[36:37], v[2:3], v[36:37]
	v_pk_fma_f32 v[16:17], v[12:13], v[16:17], v[12:13]
	v_pk_fma_f32 v[20:21], v[14:15], v[20:21], v[14:15]
	v_pk_fma_f32 v[26:27], v[8:9], v[26:27], v[8:9]
	v_pk_fma_f32 v[28:29], v[10:11], v[28:29], v[10:11]
	v_pk_fma_f32 v[30:31], v[4:5], v[30:31], v[4:5]
	v_pk_fma_f32 v[32:33], v[6:7], v[32:33], v[6:7]
	v_pk_fma_f32 v[34:35], v[0:1], v[34:35], v[0:1]
	v_pk_fma_f32 v[36:37], v[2:3], v[36:37], v[2:3]
	v_pk_mul_f32 v[16:17], v[16:17], v[192:193] op_sel_hi:[1,0]
	v_pk_mul_f32 v[20:21], v[20:21], v[192:193] op_sel_hi:[1,0]
	v_pk_mul_f32 v[26:27], v[26:27], v[192:193] op_sel_hi:[1,0]
	v_pk_mul_f32 v[28:29], v[28:29], v[192:193] op_sel_hi:[1,0]
	v_pk_mul_f32 v[30:31], v[30:31], v[192:193] op_sel_hi:[1,0]
	v_pk_mul_f32 v[32:33], v[32:33], v[192:193] op_sel_hi:[1,0]
	v_pk_mul_f32 v[34:35], v[34:35], v[192:193] op_sel_hi:[1,0]
	v_pk_mul_f32 v[36:37], v[36:37], v[192:193] op_sel_hi:[1,0]
	v_pk_mul_f32 v[16:17], v[16:17], v[194:195] op_sel_hi:[1,0]
	v_pk_mul_f32 v[20:21], v[20:21], v[194:195] op_sel_hi:[1,0]
	v_pk_mul_f32 v[26:27], v[26:27], v[194:195] op_sel_hi:[1,0]
	v_pk_mul_f32 v[28:29], v[28:29], v[194:195] op_sel_hi:[1,0]
	v_pk_mul_f32 v[30:31], v[30:31], v[194:195] op_sel_hi:[1,0]
	v_pk_mul_f32 v[32:33], v[32:33], v[194:195] op_sel_hi:[1,0]
	v_pk_mul_f32 v[34:35], v[34:35], v[194:195] op_sel_hi:[1,0]
	v_pk_mul_f32 v[36:37], v[36:37], v[194:195] op_sel_hi:[1,0]
	v_exp_f32_e32 v16, v16
	v_exp_f32_e32 v17, v17
	v_exp_f32_e32 v20, v20
	v_exp_f32_e32 v21, v21
	v_exp_f32_e32 v26, v26
	v_exp_f32_e32 v27, v27
	v_exp_f32_e32 v28, v28
	v_exp_f32_e32 v29, v29
	v_exp_f32_e32 v30, v30
	v_exp_f32_e32 v31, v31
	v_exp_f32_e32 v32, v32
	v_exp_f32_e32 v33, v33
	v_exp_f32_e32 v34, v34
	v_exp_f32_e32 v35, v35
	v_exp_f32_e32 v36, v36
	v_exp_f32_e32 v37, v37
	v_pk_add_f32 v[16:17], v[16:17], 1.0 op_sel_hi:[1,0]
	v_pk_add_f32 v[20:21], v[20:21], 1.0 op_sel_hi:[1,0]
	v_pk_add_f32 v[26:27], v[26:27], 1.0 op_sel_hi:[1,0]
	v_pk_add_f32 v[28:29], v[28:29], 1.0 op_sel_hi:[1,0]
	v_pk_add_f32 v[30:31], v[30:31], 1.0 op_sel_hi:[1,0]
	v_pk_add_f32 v[32:33], v[32:33], 1.0 op_sel_hi:[1,0]
	v_pk_add_f32 v[34:35], v[34:35], 1.0 op_sel_hi:[1,0]
	v_pk_add_f32 v[36:37], v[36:37], 1.0 op_sel_hi:[1,0]
	v_rcp_f32_e32 v16, v16
	v_rcp_f32_e32 v17, v17
	v_rcp_f32_e32 v20, v20
	v_rcp_f32_e32 v21, v21
	v_rcp_f32_e32 v26, v26
	v_rcp_f32_e32 v27, v27
	v_rcp_f32_e32 v28, v28
	v_rcp_f32_e32 v29, v29
	v_rcp_f32_e32 v30, v30
	v_rcp_f32_e32 v31, v31
	v_rcp_f32_e32 v32, v32
	v_rcp_f32_e32 v33, v33
	v_rcp_f32_e32 v34, v34
	v_rcp_f32_e32 v35, v35
	v_rcp_f32_e32 v36, v36
	v_rcp_f32_e32 v37, v37
	v_pk_mul_f32 v[16:17], v[12:13], v[16:17]
	v_pk_mul_f32 v[20:21], v[14:15], v[20:21]
	v_pk_mul_f32 v[26:27], v[8:9], v[26:27]
	v_pk_mul_f32 v[28:29], v[10:11], v[28:29]
	v_pk_mul_f32 v[30:31], v[4:5], v[30:31]
	v_pk_mul_f32 v[32:33], v[6:7], v[32:33]
	v_pk_mul_f32 v[34:35], v[0:1], v[34:35]
	v_pk_mul_f32 v[36:37], v[2:3], v[36:37]
	v_pk_mul_f32 v[18:19], v[16:17], v[16:17]
	v_pk_mul_f32 v[22:23], v[20:21], v[20:21]
	v_add_f32_e32 v18, v18, v19
	v_add_f32_e32 v18, v22, v18
	v_pk_mul_f32 v[38:39], v[26:27], v[26:27]
	v_add_f32_e32 v18, v23, v18
	v_add_f32_e32 v18, v38, v18
	v_pk_mul_f32 v[40:41], v[28:29], v[28:29]
	v_add_f32_e32 v18, v39, v18
	v_add_f32_e32 v18, v40, v18
	v_pk_mul_f32 v[42:43], v[30:31], v[30:31]
	v_add_f32_e32 v18, v41, v18
	v_add_f32_e32 v18, v18, v42
	v_pk_mul_f32 v[44:45], v[32:33], v[32:33]
	v_add_f32_e32 v18, v43, v18
	v_add_f32_e32 v18, v44, v18
	v_pk_mul_f32 v[46:47], v[34:35], v[34:35]
	v_add_f32_e32 v18, v45, v18
	v_add_f32_e32 v18, v46, v18
	v_pk_mul_f32 v[48:49], v[36:37], v[36:37]
	v_add_f32_e32 v18, v47, v18
	v_add_f32_e32 v18, v48, v18
	v_add_f32_e32 v18, v49, v18
	v_mov_b32_e32 v19, v18
	s_nop 1
	v_permlane16_swap_b32 v18, v19
	v_lshl_add_u64 v[48:49], v[140:141], 2, s[18:19]
	v_ashrrev_i32_e32 v25, 31, v24
	v_lshlrev_b64 v[42:43], 10, v[24:25]
	v_lshlrev_b32_e32 v40, 9, v24
	s_waitcnt lgkmcnt(0)
	v_add_f32_e32 v18, v18, v19
	v_mov_b32_e32 v19, v18
	s_nop 1
	v_permlane32_swap_b32 v18, v19
	v_mov_b32_e32 v41, v141
	s_waitcnt lgkmcnt(0)
	v_add_f32_e32 v18, v18, v19
	v_fmamk_f32 v18, v18, 0x3c800000, v188
	v_cmp_gt_f32_e32 vcc, s13, v18
	v_mul_f32_e32 v19, 0x4b800000, v18
	s_nop 0
	v_cndmask_b32_e32 v18, v18, v19, vcc
	v_rsq_f32_e32 v18, v18
	s_nop 0
	v_mul_f32_e32 v19, 0x45800000, v18
	v_cndmask_b32_e32 v38, v18, v19, vcc
	v_pk_mul_f32 v[44:45], v[16:17], v[38:39] op_sel_hi:[1,0]
	v_pk_mul_f32 v[46:47], v[20:21], v[38:39] op_sel_hi:[1,0]
	v_mov_b64_e32 v[16:17], v[208:209]
	v_mov_b64_e32 v[18:19], v[210:211]
	v_mov_b64_e32 v[20:21], v[204:205]
	v_mov_b64_e32 v[22:23], v[206:207]
	v_pk_mul_f32 v[26:27], v[26:27], v[38:39] op_sel_hi:[1,0]
	v_pk_mul_f32 v[28:29], v[28:29], v[38:39] op_sel_hi:[1,0]
	v_pk_mul_f32 v[16:17], v[16:17], v[26:27]
	v_lshl_add_u64 v[26:27], s[46:47], 0, v[42:43]
	v_pk_mul_f32 v[22:23], v[22:23], v[46:47]
	v_pk_mul_f32 v[20:21], v[20:21], v[44:45]
	v_pk_mul_f32 v[18:19], v[18:19], v[28:29]
	v_lshl_add_u64 v[28:29], v[140:141], 1, v[26:27]
	v_lshl_add_u64 v[26:27], v[40:41], 2, s[56:57]
	v_cvt_pk_bf16_f32 v42, v20, v21
	v_cvt_pk_bf16_f32 v43, v22, v23
	v_cvt_pk_bf16_f32 v44, v16, v17
	v_cvt_pk_bf16_f32 v45, v18, v19
	global_store_dwordx4 v[28:29], v[42:45], off
	s_and_saveexec_b64 s[0:1], s[10:11]
	s_cbranch_execz .LBB0_348
	v_lshl_add_u64 v[40:41], v[140:141], 2, v[26:27]
	v_lshl_add_u64 v[42:43], v[40:41], 0, s[70:71]
	v_add_co_u32_e32 v40, vcc, 0x2108000, v40
	s_nop 1
	v_addc_co_u32_e32 v41, vcc, 0, v41, vcc
	global_store_dwordx4 v[40:41], v[20:23], off
	global_store_dwordx4 v[42:43], v[16:19], off offset:16
